# GEMM k-loops: per-tile combined lane mask selects an unguarded copy of the load sequence when every lane is valid; guarded sequence otherwise
# baseline (speedup 1.0000x reference)
.LBB0_266:
	s_or_b64 exec, exec, s[28:29]
	s_and_b32 s3, s37, 0xffffff80
	v_or_b32_e32 v2, s3, v223
	v_ashrrev_i32_e32 v3, 31, v2
	v_lshlrev_b64 v[2:3], 11, v[2:3]
	v_lshl_add_u64 v[200:201], s[82:83], 0, v[2:3]
	v_or_b32_e32 v2, s3, v224
	v_ashrrev_i32_e32 v3, 31, v2
	v_lshlrev_b64 v[2:3], 11, v[2:3]
	v_lshl_add_u64 v[202:203], s[82:83], 0, v[2:3]
	v_or_b32_e32 v2, s3, v225
	v_ashrrev_i32_e32 v3, 31, v2
	v_lshlrev_b64 v[2:3], 11, v[2:3]
	v_lshl_add_u64 v[204:205], s[82:83], 0, v[2:3]
	v_or_b32_e32 v2, s3, v1
	s_mov_b32 s3, s21
	v_ashrrev_i32_e32 v3, 31, v2
	v_lshl_add_u64 v[208:209], v[186:187], 0, s[2:3]
	global_load_dwordx4 v[246:249], v[208:209], off
	global_load_dwordx4 v[250:253], v[208:209], off offset:-16
	s_add_u32 s2, s82, s20
	v_lshlrev_b64 v[2:3], 11, v[2:3]
	v_mov_b32_e32 v65, v172
	s_addc_u32 s3, s83, 0
	v_mov_b32_e32 v63, v172
	v_mov_b32_e32 v61, v172
	v_mov_b32_e32 v59, v172
	v_lshl_add_u64 v[206:207], s[82:83], 0, v[2:3]
	v_lshl_add_u64 v[210:211], s[2:3], 0, v[64:65]
	v_lshl_add_u64 v[212:213], s[2:3], 0, v[62:63]
	v_lshl_add_u64 v[214:215], s[2:3], 0, v[60:61]
	v_lshl_add_u64 v[216:217], s[2:3], 0, v[58:59]
	s_mov_b32 s20, 0
	v_mov_b32_e32 v51, v50
	v_mov_b32_e32 v52, v50
	v_mov_b32_e32 v53, v50
	v_mov_b32_e32 v54, v50
	v_mov_b32_e32 v55, v50
	v_mov_b32_e32 v56, v50
	v_mov_b32_e32 v57, v50
	v_mov_b32_e32 v58, v50
	v_mov_b32_e32 v59, v50
	v_mov_b32_e32 v60, v50
	v_mov_b32_e32 v61, v50
	v_mov_b32_e32 v62, v50
	v_mov_b32_e32 v63, v50
	v_mov_b32_e32 v64, v50
	v_mov_b32_e32 v65, v50
	v_mov_b32_e32 v34, v50
	v_mov_b32_e32 v35, v50
	v_mov_b32_e32 v36, v50
	v_mov_b32_e32 v37, v50
	v_mov_b32_e32 v38, v50
	v_mov_b32_e32 v39, v50
	v_mov_b32_e32 v40, v50
	v_mov_b32_e32 v41, v50
	v_mov_b32_e32 v42, v50
	v_mov_b32_e32 v43, v50
	v_mov_b32_e32 v44, v50
	v_mov_b32_e32 v45, v50
	v_mov_b32_e32 v46, v50
	v_mov_b32_e32 v47, v50
	v_mov_b32_e32 v48, v50
	v_mov_b32_e32 v49, v50
	v_mov_b32_e32 v18, v50
	v_mov_b32_e32 v19, v50
	v_mov_b32_e32 v20, v50
	v_mov_b32_e32 v21, v50
	v_mov_b32_e32 v22, v50
	v_mov_b32_e32 v23, v50
	v_mov_b32_e32 v24, v50
	v_mov_b32_e32 v25, v50
	v_mov_b32_e32 v26, v50
	v_mov_b32_e32 v27, v50
	v_mov_b32_e32 v28, v50
	v_mov_b32_e32 v29, v50
	v_mov_b32_e32 v30, v50
	v_mov_b32_e32 v31, v50
	v_mov_b32_e32 v32, v50
	v_mov_b32_e32 v33, v50
	v_mov_b32_e32 v2, v50
	v_mov_b32_e32 v3, v50
	v_mov_b32_e32 v4, v50
	v_mov_b32_e32 v5, v50
	v_mov_b32_e32 v6, v50
	v_mov_b32_e32 v7, v50
	v_mov_b32_e32 v8, v50
	v_mov_b32_e32 v9, v50
	v_mov_b32_e32 v10, v50
	v_mov_b32_e32 v11, v50
	v_mov_b32_e32 v12, v50
	v_mov_b32_e32 v13, v50
	v_mov_b32_e32 v14, v50
	v_mov_b32_e32 v15, v50
	v_mov_b32_e32 v16, v50
	v_mov_b32_e32 v17, v50
	s_waitcnt lgkmcnt(0)
	s_barrier
	s_waitcnt vmcnt(0)
	v_subrev_u32_e32 v206, s82, v206
	v_add_u32_e32 v206, v206, v188
	v_subrev_u32_e32 v192, s82, v192
	v_add_u32_e32 v192, v192, v188
	v_subrev_u32_e32 v216, s82, v216
	v_add_u32_e32 v216, v216, v188
	v_subrev_u32_e32 v204, s82, v204
	v_add_u32_e32 v204, v204, v188
	v_subrev_u32_e32 v194, s82, v194
	v_add_u32_e32 v194, v194, v188
	v_subrev_u32_e32 v214, s82, v214
	v_add_u32_e32 v214, v214, v188
	v_subrev_u32_e32 v202, s82, v202
	v_add_u32_e32 v202, v202, v188
	v_subrev_u32_e32 v196, s82, v196
	v_add_u32_e32 v196, v196, v188
	v_subrev_u32_e32 v212, s82, v212
	v_add_u32_e32 v212, v212, v188
	v_subrev_u32_e32 v200, s82, v200
	v_add_u32_e32 v200, v200, v188
	v_subrev_u32_e32 v198, s82, v198
	v_add_u32_e32 v198, v198, v188
	v_subrev_u32_e32 v210, s82, v210
	v_add_u32_e32 v210, v210, v188
	s_add_u32 s84, s82, 0xa380000
	s_addc_u32 s85, s83, 0
	s_mov_b32 s86, s82
	s_mov_b32 s87, s83
	s_mov_b64 s[88:89], s[4:5]
	s_and_b64 s[88:89], s[88:89], s[6:7]
	s_and_b64 s[88:89], s[88:89], s[8:9]
	s_and_b64 s[88:89], s[88:89], s[10:11]
	s_branch .LBB0_269

.LBB0_269:
	s_waitcnt vmcnt(8)
	v_lshlrev_b32_e32 v230, 16, v66
	v_and_b32_e32 v231, 0xffff0000, v66
	v_lshlrev_b32_e32 v232, 16, v70
	v_and_b32_e32 v233, 0xffff0000, v70
	v_pk_add_f32 v[232:233], v[232:233], v[230:231] neg_lo:[0,1] neg_hi:[0,1]
	v_lshlrev_b32_e32 v234, 16, v71
	v_and_b32_e32 v235, 0xffff0000, v71
	v_lshlrev_b32_e32 v236, 16, v73
	v_and_b32_e32 v237, 0xffff0000, v73
	s_cmp_gt_u32 s20, 12
	v_pk_fma_f32 v[230:231], v[232:233], v[250:251], v[230:231]
	v_lshlrev_b32_e32 v232, 16, v67
	v_and_b32_e32 v233, 0xffff0000, v67
	v_pk_add_f32 v[234:235], v[234:235], v[232:233] neg_lo:[0,1] neg_hi:[0,1]
	v_cvt_pk_bf16_f32 v230, v230, v231
	v_pk_fma_f32 v[232:233], v[234:235], v[252:253], v[232:233]
	v_lshlrev_b32_e32 v234, 16, v72
	v_cvt_pk_bf16_f32 v231, v232, v233
	v_lshlrev_b32_e32 v232, 16, v68
	v_and_b32_e32 v233, 0xffff0000, v68
	v_and_b32_e32 v235, 0xffff0000, v72
	v_pk_add_f32 v[234:235], v[234:235], v[232:233] neg_lo:[0,1] neg_hi:[0,1]
	s_nop 0
	v_pk_fma_f32 v[232:233], v[234:235], v[246:247], v[232:233]
	v_lshlrev_b32_e32 v234, 16, v69
	v_and_b32_e32 v235, 0xffff0000, v69
	v_pk_add_f32 v[236:237], v[236:237], v[234:235] neg_lo:[0,1] neg_hi:[0,1]
	v_cvt_pk_bf16_f32 v232, v232, v233
	v_pk_fma_f32 v[234:235], v[236:237], v[248:249], v[234:235]
	v_lshlrev_b32_e32 v236, 16, v89
	v_cvt_pk_bf16_f32 v233, v234, v235
	ds_write_b128 v219, v[230:233] offset:36864
	ds_write_b128 v219, v[74:77] offset:55296
	v_lshlrev_b32_e32 v230, 16, v82
	v_and_b32_e32 v231, 0xffff0000, v82
	v_lshlrev_b32_e32 v232, 16, v86
	v_and_b32_e32 v233, 0xffff0000, v86
	v_pk_add_f32 v[232:233], v[232:233], v[230:231] neg_lo:[0,1] neg_hi:[0,1]
	v_lshlrev_b32_e32 v234, 16, v87
	v_pk_fma_f32 v[230:231], v[232:233], v[250:251], v[230:231]
	v_lshlrev_b32_e32 v232, 16, v83
	v_and_b32_e32 v233, 0xffff0000, v83
	v_and_b32_e32 v235, 0xffff0000, v87
	v_pk_add_f32 v[234:235], v[234:235], v[232:233] neg_lo:[0,1] neg_hi:[0,1]
	v_cvt_pk_bf16_f32 v230, v230, v231
	v_pk_fma_f32 v[232:233], v[234:235], v[252:253], v[232:233]
	v_lshlrev_b32_e32 v234, 16, v88
	v_cvt_pk_bf16_f32 v231, v232, v233
	v_lshlrev_b32_e32 v232, 16, v84
	v_and_b32_e32 v233, 0xffff0000, v84
	v_and_b32_e32 v235, 0xffff0000, v88
	v_pk_add_f32 v[234:235], v[234:235], v[232:233] neg_lo:[0,1] neg_hi:[0,1]
	v_and_b32_e32 v237, 0xffff0000, v89
	v_pk_fma_f32 v[232:233], v[234:235], v[246:247], v[232:233]
	v_lshlrev_b32_e32 v234, 16, v85
	v_and_b32_e32 v235, 0xffff0000, v85
	v_pk_add_f32 v[236:237], v[236:237], v[234:235] neg_lo:[0,1] neg_hi:[0,1]
	v_cvt_pk_bf16_f32 v232, v232, v233
	v_pk_fma_f32 v[234:235], v[236:237], v[248:249], v[234:235]
	v_lshlrev_b32_e32 v236, 16, v97
	v_cvt_pk_bf16_f32 v233, v234, v235
	ds_write_b128 v219, v[230:233] offset:41472
	ds_write_b128 v219, v[78:81] offset:59904
	v_lshlrev_b32_e32 v230, 16, v90
	v_and_b32_e32 v231, 0xffff0000, v90
	v_lshlrev_b32_e32 v232, 16, v94
	v_and_b32_e32 v233, 0xffff0000, v94
	v_pk_add_f32 v[232:233], v[232:233], v[230:231] neg_lo:[0,1] neg_hi:[0,1]
	v_lshlrev_b32_e32 v234, 16, v95
	v_pk_fma_f32 v[230:231], v[232:233], v[250:251], v[230:231]
	v_lshlrev_b32_e32 v232, 16, v91
	v_and_b32_e32 v233, 0xffff0000, v91
	v_and_b32_e32 v235, 0xffff0000, v95
	v_pk_add_f32 v[234:235], v[234:235], v[232:233] neg_lo:[0,1] neg_hi:[0,1]
	v_cvt_pk_bf16_f32 v230, v230, v231
	v_pk_fma_f32 v[232:233], v[234:235], v[252:253], v[232:233]
	v_lshlrev_b32_e32 v234, 16, v96
	v_cvt_pk_bf16_f32 v231, v232, v233
	v_lshlrev_b32_e32 v232, 16, v92
	v_and_b32_e32 v233, 0xffff0000, v92
	v_and_b32_e32 v235, 0xffff0000, v96
	v_pk_add_f32 v[234:235], v[234:235], v[232:233] neg_lo:[0,1] neg_hi:[0,1]
	v_and_b32_e32 v237, 0xffff0000, v97
	v_pk_fma_f32 v[232:233], v[234:235], v[246:247], v[232:233]
	v_lshlrev_b32_e32 v234, 16, v93
	v_and_b32_e32 v235, 0xffff0000, v93
	v_pk_add_f32 v[236:237], v[236:237], v[234:235] neg_lo:[0,1] neg_hi:[0,1]
	v_cvt_pk_bf16_f32 v232, v232, v233
	v_pk_fma_f32 v[234:235], v[236:237], v[248:249], v[234:235]
	s_nop 0
	v_cvt_pk_bf16_f32 v233, v234, v235
	ds_write_b128 v219, v[230:233] offset:46080
	ds_write_b128 v219, v[98:101] offset:64512
	v_lshlrev_b32_e32 v230, 16, v102
	v_and_b32_e32 v231, 0xffff0000, v102
	v_lshlrev_b32_e32 v232, 16, v106
	v_and_b32_e32 v233, 0xffff0000, v106
	v_pk_add_f32 v[232:233], v[232:233], v[230:231] neg_lo:[0,1] neg_hi:[0,1]
	s_nop 0
	v_pk_fma_f32 v[166:167], v[232:233], v[250:251], v[230:231]
	v_lshlrev_b32_e32 v230, 16, v103
	v_and_b32_e32 v231, 0xffff0000, v103
	v_lshlrev_b32_e32 v232, 16, v107
	v_and_b32_e32 v233, 0xffff0000, v107
	v_pk_add_f32 v[232:233], v[232:233], v[230:231] neg_lo:[0,1] neg_hi:[0,1]
	v_cvt_pk_bf16_f32 v166, v166, v167
	v_pk_fma_f32 v[168:169], v[232:233], v[252:253], v[230:231]
	v_lshlrev_b32_e32 v230, 16, v108
	v_cvt_pk_bf16_f32 v167, v168, v169
	v_lshlrev_b32_e32 v168, 16, v104
	v_and_b32_e32 v169, 0xffff0000, v104
	v_and_b32_e32 v231, 0xffff0000, v108
	v_pk_add_f32 v[230:231], v[230:231], v[168:169] neg_lo:[0,1] neg_hi:[0,1]
	s_nop 0
	v_pk_fma_f32 v[162:163], v[230:231], v[246:247], v[168:169]
	v_lshlrev_b32_e32 v230, 16, v109
	v_cvt_pk_bf16_f32 v168, v162, v163
	v_lshlrev_b32_e32 v162, 16, v105
	v_and_b32_e32 v163, 0xffff0000, v105
	v_and_b32_e32 v231, 0xffff0000, v109
	v_pk_add_f32 v[230:231], v[230:231], v[162:163] neg_lo:[0,1] neg_hi:[0,1]
	s_nop 0
	v_pk_fma_f32 v[162:163], v[230:231], v[248:249], v[162:163]
	s_nop 0
	v_cvt_pk_bf16_f32 v169, v162, v163
	ds_write_b128 v219, v[166:169] offset:50688
	ds_write_b128 v221, v[110:113] offset:13824
	s_cbranch_scc1 .LBB0_279
	global_load_dwordx4 v[246:249], v[208:209], off offset:256
	global_load_dwordx4 v[250:253], v[208:209], off offset:240
	s_cmp_eq_u64 s[88:89], exec
	s_cbranch_scc1 .Lgf_1
	global_load_dwordx4 v[66:69], v206, s[84:85] offset:384
	global_load_dwordx4 v[70:73], v192, s[86:87] offset:384
	s_and_saveexec_b64 s[2:3], s[4:5]
	s_cbranch_execz .LBB0_272
	global_load_dwordx4 v[74:77], v216, s[86:87] offset:384

.LBB0_279:
	ds_read_b128 v[162:165], v227
	ds_read_b128 v[166:169], v228 offset:18432
	ds_read_b128 v[230:233], v228 offset:23040
	s_cmp_gt_u32 s20, 13
	s_cselect_b64 s[2:3], -1, 0
	s_and_b64 vcc, exec, s[2:3]
	s_waitcnt lgkmcnt(1)
	v_mfma_f32_32x32x16_bf16 v[50:65], v[162:165], v[166:169], v[50:65]
	s_waitcnt lgkmcnt(0)
	v_mfma_f32_32x32x16_bf16 v[34:49], v[162:165], v[230:233], v[34:49]
	ds_read_b128 v[162:165], v227 offset:4608
	s_waitcnt lgkmcnt(0)
	v_mfma_f32_32x32x16_bf16 v[18:33], v[162:165], v[166:169], v[18:33]
	v_mfma_f32_32x32x16_bf16 v[2:17], v[162:165], v[230:233], v[2:17]
	ds_read_b128 v[162:165], v227 offset:32
	ds_read_b128 v[166:169], v228 offset:18464
	ds_read_b128 v[230:233], v228 offset:23072
	s_waitcnt lgkmcnt(1)
	v_mfma_f32_32x32x16_bf16 v[50:65], v[162:165], v[166:169], v[50:65]
	s_waitcnt lgkmcnt(0)
	v_mfma_f32_32x32x16_bf16 v[34:49], v[162:165], v[230:233], v[34:49]
	ds_read_b128 v[162:165], v227 offset:4640
	s_waitcnt lgkmcnt(0)
	v_mfma_f32_32x32x16_bf16 v[18:33], v[162:165], v[166:169], v[18:33]
	v_mfma_f32_32x32x16_bf16 v[2:17], v[162:165], v[230:233], v[2:17]
	ds_read_b128 v[162:165], v227 offset:64
	ds_read_b128 v[166:169], v228 offset:18496
	ds_read_b128 v[230:233], v228 offset:23104
	s_waitcnt lgkmcnt(1)
	v_mfma_f32_32x32x16_bf16 v[50:65], v[162:165], v[166:169], v[50:65]
	s_waitcnt lgkmcnt(0)
	v_mfma_f32_32x32x16_bf16 v[34:49], v[162:165], v[230:233], v[34:49]
	ds_read_b128 v[162:165], v227 offset:4672
	s_waitcnt lgkmcnt(0)
	v_mfma_f32_32x32x16_bf16 v[18:33], v[162:165], v[166:169], v[18:33]
	v_mfma_f32_32x32x16_bf16 v[2:17], v[162:165], v[230:233], v[2:17]
	ds_read_b128 v[162:165], v227 offset:96
	ds_read_b128 v[166:169], v228 offset:18528
	ds_read_b128 v[230:233], v228 offset:23136
	s_waitcnt lgkmcnt(1)
	v_mfma_f32_32x32x16_bf16 v[50:65], v[162:165], v[166:169], v[50:65]
	s_waitcnt lgkmcnt(0)
	v_mfma_f32_32x32x16_bf16 v[34:49], v[162:165], v[230:233], v[34:49]
	ds_read_b128 v[162:165], v227 offset:4704
	s_waitcnt lgkmcnt(0)
	s_barrier
	v_mfma_f32_32x32x16_bf16 v[18:33], v[162:165], v[166:169], v[18:33]
	v_mfma_f32_32x32x16_bf16 v[2:17], v[162:165], v[230:233], v[2:17]
	s_cbranch_vccnz .LBB0_268
	s_waitcnt vmcnt(8)
	v_lshlrev_b32_e32 v230, 16, v114
	v_and_b32_e32 v231, 0xffff0000, v114
	v_lshlrev_b32_e32 v232, 16, v118
	v_and_b32_e32 v233, 0xffff0000, v118
	v_pk_add_f32 v[232:233], v[232:233], v[230:231] neg_lo:[0,1] neg_hi:[0,1]
	v_lshlrev_b32_e32 v234, 16, v119
	v_and_b32_e32 v235, 0xffff0000, v119
	v_lshlrev_b32_e32 v236, 16, v121
	v_and_b32_e32 v237, 0xffff0000, v121
	s_cmp_gt_u32 s20, 11
	v_pk_fma_f32 v[230:231], v[232:233], v[250:251], v[230:231]
	v_lshlrev_b32_e32 v232, 16, v115
	v_and_b32_e32 v233, 0xffff0000, v115
	v_pk_add_f32 v[234:235], v[234:235], v[232:233] neg_lo:[0,1] neg_hi:[0,1]
	v_cvt_pk_bf16_f32 v230, v230, v231
	v_pk_fma_f32 v[232:233], v[234:235], v[252:253], v[232:233]
	v_lshlrev_b32_e32 v234, 16, v120
	v_cvt_pk_bf16_f32 v231, v232, v233
	v_lshlrev_b32_e32 v232, 16, v116
	v_and_b32_e32 v233, 0xffff0000, v116
	v_and_b32_e32 v235, 0xffff0000, v120
	v_pk_add_f32 v[234:235], v[234:235], v[232:233] neg_lo:[0,1] neg_hi:[0,1]
	s_nop 0
	v_pk_fma_f32 v[232:233], v[234:235], v[246:247], v[232:233]
	v_lshlrev_b32_e32 v234, 16, v117
	v_and_b32_e32 v235, 0xffff0000, v117
	v_pk_add_f32 v[236:237], v[236:237], v[234:235] neg_lo:[0,1] neg_hi:[0,1]
	v_cvt_pk_bf16_f32 v232, v232, v233
	v_pk_fma_f32 v[234:235], v[236:237], v[248:249], v[234:235]
	v_lshlrev_b32_e32 v236, 16, v137
	v_cvt_pk_bf16_f32 v233, v234, v235
	ds_write_b128 v219, v[230:233]
	ds_write_b128 v219, v[122:125] offset:18432
	v_lshlrev_b32_e32 v230, 16, v130
	v_and_b32_e32 v231, 0xffff0000, v130
	v_lshlrev_b32_e32 v232, 16, v134
	v_and_b32_e32 v233, 0xffff0000, v134
	v_pk_add_f32 v[232:233], v[232:233], v[230:231] neg_lo:[0,1] neg_hi:[0,1]
	v_lshlrev_b32_e32 v234, 16, v135
	v_pk_fma_f32 v[230:231], v[232:233], v[250:251], v[230:231]
	v_lshlrev_b32_e32 v232, 16, v131
	v_and_b32_e32 v233, 0xffff0000, v131
	v_and_b32_e32 v235, 0xffff0000, v135
	v_pk_add_f32 v[234:235], v[234:235], v[232:233] neg_lo:[0,1] neg_hi:[0,1]
	v_cvt_pk_bf16_f32 v230, v230, v231
	v_pk_fma_f32 v[232:233], v[234:235], v[252:253], v[232:233]
	v_lshlrev_b32_e32 v234, 16, v136
	v_cvt_pk_bf16_f32 v231, v232, v233
	v_lshlrev_b32_e32 v232, 16, v132
	v_and_b32_e32 v233, 0xffff0000, v132
	v_and_b32_e32 v235, 0xffff0000, v136
	v_pk_add_f32 v[234:235], v[234:235], v[232:233] neg_lo:[0,1] neg_hi:[0,1]
	v_and_b32_e32 v237, 0xffff0000, v137
	v_pk_fma_f32 v[232:233], v[234:235], v[246:247], v[232:233]
	v_lshlrev_b32_e32 v234, 16, v133
	v_and_b32_e32 v235, 0xffff0000, v133
	v_pk_add_f32 v[236:237], v[236:237], v[234:235] neg_lo:[0,1] neg_hi:[0,1]
	v_cvt_pk_bf16_f32 v232, v232, v233
	v_pk_fma_f32 v[234:235], v[236:237], v[248:249], v[234:235]
	v_lshlrev_b32_e32 v236, 16, v145
	v_cvt_pk_bf16_f32 v233, v234, v235
	ds_write_b128 v219, v[230:233] offset:4608
	ds_write_b128 v219, v[126:129] offset:23040
	v_lshlrev_b32_e32 v230, 16, v138
	v_and_b32_e32 v231, 0xffff0000, v138
	v_lshlrev_b32_e32 v232, 16, v142
	v_and_b32_e32 v233, 0xffff0000, v142
	v_pk_add_f32 v[232:233], v[232:233], v[230:231] neg_lo:[0,1] neg_hi:[0,1]
	v_lshlrev_b32_e32 v234, 16, v143
	v_pk_fma_f32 v[230:231], v[232:233], v[250:251], v[230:231]
	v_lshlrev_b32_e32 v232, 16, v139
	v_and_b32_e32 v233, 0xffff0000, v139
	v_and_b32_e32 v235, 0xffff0000, v143
	v_pk_add_f32 v[234:235], v[234:235], v[232:233] neg_lo:[0,1] neg_hi:[0,1]
	v_cvt_pk_bf16_f32 v230, v230, v231
	v_pk_fma_f32 v[232:233], v[234:235], v[252:253], v[232:233]
	v_lshlrev_b32_e32 v234, 16, v144
	v_cvt_pk_bf16_f32 v231, v232, v233
	v_lshlrev_b32_e32 v232, 16, v140
	v_and_b32_e32 v233, 0xffff0000, v140
	v_and_b32_e32 v235, 0xffff0000, v144
	v_pk_add_f32 v[234:235], v[234:235], v[232:233] neg_lo:[0,1] neg_hi:[0,1]
	v_and_b32_e32 v237, 0xffff0000, v145
	v_pk_fma_f32 v[232:233], v[234:235], v[246:247], v[232:233]
	v_lshlrev_b32_e32 v234, 16, v141
	v_and_b32_e32 v235, 0xffff0000, v141
	v_pk_add_f32 v[236:237], v[236:237], v[234:235] neg_lo:[0,1] neg_hi:[0,1]
	v_cvt_pk_bf16_f32 v232, v232, v233
	v_pk_fma_f32 v[234:235], v[236:237], v[248:249], v[234:235]
	s_nop 0
	v_cvt_pk_bf16_f32 v233, v234, v235
	ds_write_b128 v219, v[230:233] offset:9216
	ds_write_b128 v219, v[146:149] offset:27648
	v_lshlrev_b32_e32 v230, 16, v150
	v_and_b32_e32 v231, 0xffff0000, v150
	v_lshlrev_b32_e32 v232, 16, v154
	v_and_b32_e32 v233, 0xffff0000, v154
	v_pk_add_f32 v[232:233], v[232:233], v[230:231] neg_lo:[0,1] neg_hi:[0,1]
	s_nop 0
	v_pk_fma_f32 v[166:167], v[232:233], v[250:251], v[230:231]
	v_lshlrev_b32_e32 v230, 16, v151
	v_and_b32_e32 v231, 0xffff0000, v151
	v_lshlrev_b32_e32 v232, 16, v155
	v_and_b32_e32 v233, 0xffff0000, v155
	v_pk_add_f32 v[232:233], v[232:233], v[230:231] neg_lo:[0,1] neg_hi:[0,1]
	v_cvt_pk_bf16_f32 v166, v166, v167
	v_pk_fma_f32 v[168:169], v[232:233], v[252:253], v[230:231]
	v_lshlrev_b32_e32 v230, 16, v156
	v_cvt_pk_bf16_f32 v167, v168, v169
	v_lshlrev_b32_e32 v168, 16, v152
	v_and_b32_e32 v169, 0xffff0000, v152
	v_and_b32_e32 v231, 0xffff0000, v156
	v_pk_add_f32 v[230:231], v[230:231], v[168:169] neg_lo:[0,1] neg_hi:[0,1]
	s_nop 0
	v_pk_fma_f32 v[162:163], v[230:231], v[246:247], v[168:169]
	v_lshlrev_b32_e32 v230, 16, v157
	v_cvt_pk_bf16_f32 v168, v162, v163
	v_lshlrev_b32_e32 v162, 16, v153
	v_and_b32_e32 v163, 0xffff0000, v153
	v_and_b32_e32 v231, 0xffff0000, v157
	v_pk_add_f32 v[230:231], v[230:231], v[162:163] neg_lo:[0,1] neg_hi:[0,1]
	s_nop 0
	v_pk_fma_f32 v[162:163], v[230:231], v[248:249], v[162:163]
	s_nop 0
	v_cvt_pk_bf16_f32 v169, v162, v163
	ds_write_b128 v219, v[166:169] offset:13824
	ds_write_b128 v219, v[158:161] offset:32256
	global_load_dwordx4 v[246:249], v[208:209], off offset:512
	global_load_dwordx4 v[250:253], v[208:209], off offset:496
	s_cbranch_scc1 .Lmixpf_a_last
	s_cmp_eq_u64 s[88:89], exec
	s_cbranch_scc1 .Lgf_2
	global_load_dwordx4 v[114:117], v206, s[84:85] offset:512
	global_load_dwordx4 v[118:121], v192, s[86:87] offset:512
	s_and_saveexec_b64 s[28:29], s[4:5]
	s_cbranch_execz .LBB0_283
	global_load_dwordx4 v[122:125], v216, s[86:87] offset:512

.Lgf_1:
	global_load_dwordx4 v[66:69], v206, s[84:85] offset:384
	global_load_dwordx4 v[70:73], v192, s[86:87] offset:384
	global_load_dwordx4 v[74:77], v216, s[86:87] offset:384
	global_load_dwordx4 v[82:85], v204, s[84:85] offset:384
	global_load_dwordx4 v[86:89], v194, s[86:87] offset:384
	global_load_dwordx4 v[78:81], v214, s[86:87] offset:384
	global_load_dwordx4 v[90:93], v202, s[84:85] offset:384
	global_load_dwordx4 v[94:97], v196, s[86:87] offset:384
	global_load_dwordx4 v[98:101], v212, s[86:87] offset:384
	global_load_dwordx4 v[102:105], v200, s[84:85] offset:384
	global_load_dwordx4 v[106:109], v198, s[86:87] offset:384
	global_load_dwordx4 v[110:113], v210, s[86:87] offset:384
	s_branch .LBB0_279
.Lgf_2:
	global_load_dwordx4 v[114:117], v206, s[84:85] offset:512
	global_load_dwordx4 v[118:121], v192, s[86:87] offset:512
	global_load_dwordx4 v[122:125], v216, s[86:87] offset:512
	global_load_dwordx4 v[130:133], v204, s[84:85] offset:512
	global_load_dwordx4 v[134:137], v194, s[86:87] offset:512
	global_load_dwordx4 v[126:129], v214, s[86:87] offset:512
	global_load_dwordx4 v[138:141], v202, s[84:85] offset:512
	global_load_dwordx4 v[142:145], v196, s[86:87] offset:512
	global_load_dwordx4 v[146:149], v212, s[86:87] offset:512
	global_load_dwordx4 v[150:153], v200, s[84:85] offset:512
	global_load_dwordx4 v[154:157], v198, s[86:87] offset:512
	global_load_dwordx4 v[158:161], v210, s[86:87] offset:512
	s_branch .LBB0_268

.LBB0_672:
	s_or_b64 exec, exec, s[22:23]
	s_lshl_b32 s22, s28, 11
	s_and_b32 s22, s22, 0x1c0000
	s_add_u32 s2, s26, s2
	v_lshl_or_b32 v4, v171, 1, s22
	v_mov_b32_e32 v5, v172
	v_mov_b32_e32 v165, v172
	s_addc_u32 s3, s27, s3
	v_mov_b32_e32 v163, v172
	v_mov_b32_e32 v63, v172
	v_lshl_add_u64 v[194:195], v[178:179], 0, s[14:15]
	global_load_dwordx4 v[246:249], v[194:195], off
	global_load_dwordx4 v[250:253], v[194:195], off offset:-16
	v_lshl_add_u64 v[196:197], s[2:3], 0, v[164:165]
	v_lshl_add_u64 v[198:199], s[82:83], 0, v[166:167]
	v_lshl_add_u64 v[200:201], s[82:83], 0, v[60:61]
	v_lshl_add_u64 v[202:203], s[2:3], 0, v[162:163]
	v_lshl_add_u64 v[204:205], s[82:83], 0, v[64:65]
	v_lshl_add_u64 v[206:207], s[2:3], 0, v[62:63]
	v_lshl_add_u64 v[208:209], s[82:83], 0, v[58:59]
	v_lshl_add_u64 v[210:211], s[2:3], 0, v[4:5]
	s_mov_b32 s14, 0
	v_mov_b32_e32 v3, v2
	v_mov_b32_e32 v4, v2
	v_mov_b32_e32 v5, v2
	v_mov_b32_e32 v6, v2
	v_mov_b32_e32 v7, v2
	v_mov_b32_e32 v8, v2
	v_mov_b32_e32 v9, v2
	v_mov_b32_e32 v10, v2
	v_mov_b32_e32 v11, v2
	v_mov_b32_e32 v12, v2
	v_mov_b32_e32 v13, v2
	v_mov_b32_e32 v14, v2
	v_mov_b32_e32 v15, v2
	v_mov_b32_e32 v16, v2
	v_mov_b32_e32 v17, v2
	v_mov_b32_e32 v18, v2
	v_mov_b32_e32 v19, v2
	v_mov_b32_e32 v20, v2
	v_mov_b32_e32 v21, v2
	v_mov_b32_e32 v22, v2
	v_mov_b32_e32 v23, v2
	v_mov_b32_e32 v24, v2
	v_mov_b32_e32 v25, v2
	v_mov_b32_e32 v26, v2
	v_mov_b32_e32 v27, v2
	v_mov_b32_e32 v28, v2
	v_mov_b32_e32 v29, v2
	v_mov_b32_e32 v30, v2
	v_mov_b32_e32 v31, v2
	v_mov_b32_e32 v32, v2
	v_mov_b32_e32 v33, v2
	v_mov_b32_e32 v34, v2
	v_mov_b32_e32 v35, v2
	v_mov_b32_e32 v36, v2
	v_mov_b32_e32 v37, v2
	v_mov_b32_e32 v38, v2
	v_mov_b32_e32 v39, v2
	v_mov_b32_e32 v40, v2
	v_mov_b32_e32 v41, v2
	v_mov_b32_e32 v42, v2
	v_mov_b32_e32 v43, v2
	v_mov_b32_e32 v44, v2
	v_mov_b32_e32 v45, v2
	v_mov_b32_e32 v46, v2
	v_mov_b32_e32 v47, v2
	v_mov_b32_e32 v48, v2
	v_mov_b32_e32 v49, v2
	v_mov_b32_e32 v50, v2
	v_mov_b32_e32 v51, v2
	v_mov_b32_e32 v52, v2
	v_mov_b32_e32 v53, v2
	v_mov_b32_e32 v54, v2
	v_mov_b32_e32 v55, v2
	v_mov_b32_e32 v56, v2
	v_mov_b32_e32 v57, v2
	v_mov_b32_e32 v58, v2
	v_mov_b32_e32 v59, v2
	v_mov_b32_e32 v60, v2
	v_mov_b32_e32 v61, v2
	v_mov_b32_e32 v62, v2
	v_mov_b32_e32 v63, v2
	v_mov_b32_e32 v64, v2
	v_mov_b32_e32 v65, v2
	s_waitcnt lgkmcnt(0)
	s_barrier
	s_waitcnt vmcnt(0)
	v_subrev_u32_e32 v200, s82, v200
	v_add_u32_e32 v200, v200, v180
	v_subrev_u32_e32 v186, s82, v186
	v_add_u32_e32 v186, v186, v180
	v_subrev_u32_e32 v210, s82, v210
	v_add_u32_e32 v210, v210, v180
	v_subrev_u32_e32 v208, s82, v208
	v_add_u32_e32 v208, v208, v180
	v_subrev_u32_e32 v188, s82, v188
	v_add_u32_e32 v188, v188, v180
	v_subrev_u32_e32 v206, s82, v206
	v_add_u32_e32 v206, v206, v180
	v_subrev_u32_e32 v204, s82, v204
	v_add_u32_e32 v204, v204, v180
	v_subrev_u32_e32 v190, s82, v190
	v_add_u32_e32 v190, v190, v180
	v_subrev_u32_e32 v202, s82, v202
	v_add_u32_e32 v202, v202, v180
	v_subrev_u32_e32 v198, s82, v198
	v_add_u32_e32 v198, v198, v180
	v_subrev_u32_e32 v192, s82, v192
	v_add_u32_e32 v192, v192, v180
	v_subrev_u32_e32 v196, s82, v196
	v_add_u32_e32 v196, v196, v180
	s_add_u32 s84, s82, 0xa380000
	s_addc_u32 s85, s83, 0
	s_mov_b32 s86, s82
	s_mov_b32 s87, s83
	s_mov_b64 s[88:89], s[0:1]
	s_and_b64 s[88:89], s[88:89], s[4:5]
	s_and_b64 s[88:89], s[88:89], s[6:7]
	s_branch .LBB0_675

.LBB0_675:
	s_waitcnt vmcnt(8)
	v_lshlrev_b32_e32 v234, 16, v66
	v_and_b32_e32 v235, 0xffff0000, v66
	v_lshlrev_b32_e32 v236, 16, v70
	v_and_b32_e32 v237, 0xffff0000, v70
	v_pk_add_f32 v[236:237], v[236:237], v[234:235] neg_lo:[0,1] neg_hi:[0,1]
	v_lshlrev_b32_e32 v238, 16, v71
	v_and_b32_e32 v239, 0xffff0000, v71
	v_lshlrev_b32_e32 v240, 16, v73
	v_and_b32_e32 v241, 0xffff0000, v73
	s_cmp_gt_u32 s14, 12
	v_pk_fma_f32 v[234:235], v[236:237], v[250:251], v[234:235]
	v_lshlrev_b32_e32 v236, 16, v67
	v_and_b32_e32 v237, 0xffff0000, v67
	v_pk_add_f32 v[238:239], v[238:239], v[236:237] neg_lo:[0,1] neg_hi:[0,1]
	v_cvt_pk_bf16_f32 v234, v234, v235
	v_pk_fma_f32 v[236:237], v[238:239], v[252:253], v[236:237]
	v_lshlrev_b32_e32 v238, 16, v72
	v_cvt_pk_bf16_f32 v235, v236, v237
	v_lshlrev_b32_e32 v236, 16, v68
	v_and_b32_e32 v237, 0xffff0000, v68
	v_and_b32_e32 v239, 0xffff0000, v72
	v_pk_add_f32 v[238:239], v[238:239], v[236:237] neg_lo:[0,1] neg_hi:[0,1]
	s_nop 0
	v_pk_fma_f32 v[236:237], v[238:239], v[246:247], v[236:237]
	v_lshlrev_b32_e32 v238, 16, v69
	v_and_b32_e32 v239, 0xffff0000, v69
	v_pk_add_f32 v[240:241], v[240:241], v[238:239] neg_lo:[0,1] neg_hi:[0,1]
	v_cvt_pk_bf16_f32 v236, v236, v237
	v_pk_fma_f32 v[238:239], v[240:241], v[248:249], v[238:239]
	v_lshlrev_b32_e32 v240, 16, v85
	v_cvt_pk_bf16_f32 v237, v238, v239
	ds_write_b128 v213, v[234:237] offset:36864
	ds_write_b128 v213, v[74:77] offset:55296
	v_lshlrev_b32_e32 v234, 16, v78
	v_and_b32_e32 v235, 0xffff0000, v78
	v_lshlrev_b32_e32 v236, 16, v82
	v_and_b32_e32 v237, 0xffff0000, v82
	v_pk_add_f32 v[236:237], v[236:237], v[234:235] neg_lo:[0,1] neg_hi:[0,1]
	v_lshlrev_b32_e32 v238, 16, v83
	v_pk_fma_f32 v[234:235], v[236:237], v[250:251], v[234:235]
	v_lshlrev_b32_e32 v236, 16, v79
	v_and_b32_e32 v237, 0xffff0000, v79
	v_and_b32_e32 v239, 0xffff0000, v83
	v_pk_add_f32 v[238:239], v[238:239], v[236:237] neg_lo:[0,1] neg_hi:[0,1]
	v_cvt_pk_bf16_f32 v234, v234, v235
	v_pk_fma_f32 v[236:237], v[238:239], v[252:253], v[236:237]
	v_lshlrev_b32_e32 v238, 16, v84
	v_cvt_pk_bf16_f32 v235, v236, v237
	v_lshlrev_b32_e32 v236, 16, v80
	v_and_b32_e32 v237, 0xffff0000, v80
	v_and_b32_e32 v239, 0xffff0000, v84
	v_pk_add_f32 v[238:239], v[238:239], v[236:237] neg_lo:[0,1] neg_hi:[0,1]
	v_and_b32_e32 v241, 0xffff0000, v85
	v_pk_fma_f32 v[236:237], v[238:239], v[246:247], v[236:237]
	v_lshlrev_b32_e32 v238, 16, v81
	v_and_b32_e32 v239, 0xffff0000, v81
	v_pk_add_f32 v[240:241], v[240:241], v[238:239] neg_lo:[0,1] neg_hi:[0,1]
	v_cvt_pk_bf16_f32 v236, v236, v237
	v_pk_fma_f32 v[238:239], v[240:241], v[248:249], v[238:239]
	v_lshlrev_b32_e32 v240, 16, v101
	v_cvt_pk_bf16_f32 v237, v238, v239
	ds_write_b128 v213, v[234:237] offset:41472
	ds_write_b128 v213, v[86:89] offset:59904
	v_lshlrev_b32_e32 v234, 16, v94
	v_and_b32_e32 v235, 0xffff0000, v94
	v_lshlrev_b32_e32 v236, 16, v98
	v_and_b32_e32 v237, 0xffff0000, v98
	v_pk_add_f32 v[236:237], v[236:237], v[234:235] neg_lo:[0,1] neg_hi:[0,1]
	v_lshlrev_b32_e32 v238, 16, v99
	v_pk_fma_f32 v[234:235], v[236:237], v[250:251], v[234:235]
	v_lshlrev_b32_e32 v236, 16, v95
	v_and_b32_e32 v237, 0xffff0000, v95
	v_and_b32_e32 v239, 0xffff0000, v99
	v_pk_add_f32 v[238:239], v[238:239], v[236:237] neg_lo:[0,1] neg_hi:[0,1]
	v_cvt_pk_bf16_f32 v234, v234, v235
	v_pk_fma_f32 v[236:237], v[238:239], v[252:253], v[236:237]
	v_lshlrev_b32_e32 v238, 16, v100
	v_cvt_pk_bf16_f32 v235, v236, v237
	v_lshlrev_b32_e32 v236, 16, v96
	v_and_b32_e32 v237, 0xffff0000, v96
	v_and_b32_e32 v239, 0xffff0000, v100
	v_pk_add_f32 v[238:239], v[238:239], v[236:237] neg_lo:[0,1] neg_hi:[0,1]
	v_and_b32_e32 v241, 0xffff0000, v101
	v_pk_fma_f32 v[236:237], v[238:239], v[246:247], v[236:237]
	v_lshlrev_b32_e32 v238, 16, v97
	v_and_b32_e32 v239, 0xffff0000, v97
	v_pk_add_f32 v[240:241], v[240:241], v[238:239] neg_lo:[0,1] neg_hi:[0,1]
	v_cvt_pk_bf16_f32 v236, v236, v237
	v_pk_fma_f32 v[238:239], v[240:241], v[248:249], v[238:239]
	s_nop 0
	v_cvt_pk_bf16_f32 v237, v238, v239
	ds_write_b128 v213, v[234:237] offset:46080
	ds_write_b128 v213, v[90:93] offset:64512
	v_lshlrev_b32_e32 v234, 16, v102
	v_and_b32_e32 v235, 0xffff0000, v102
	v_lshlrev_b32_e32 v236, 16, v106
	v_and_b32_e32 v237, 0xffff0000, v106
	v_pk_add_f32 v[236:237], v[236:237], v[234:235] neg_lo:[0,1] neg_hi:[0,1]
	s_nop 0
	v_pk_fma_f32 v[166:167], v[236:237], v[250:251], v[234:235]
	v_lshlrev_b32_e32 v234, 16, v103
	v_and_b32_e32 v235, 0xffff0000, v103
	v_lshlrev_b32_e32 v236, 16, v107
	v_and_b32_e32 v237, 0xffff0000, v107
	v_pk_add_f32 v[236:237], v[236:237], v[234:235] neg_lo:[0,1] neg_hi:[0,1]
	v_cvt_pk_bf16_f32 v166, v166, v167
	v_pk_fma_f32 v[168:169], v[236:237], v[252:253], v[234:235]
	v_lshlrev_b32_e32 v234, 16, v108
	v_cvt_pk_bf16_f32 v167, v168, v169
	v_lshlrev_b32_e32 v168, 16, v104
	v_and_b32_e32 v169, 0xffff0000, v104
	v_and_b32_e32 v235, 0xffff0000, v108
	v_pk_add_f32 v[234:235], v[234:235], v[168:169] neg_lo:[0,1] neg_hi:[0,1]
	s_nop 0
	v_pk_fma_f32 v[162:163], v[234:235], v[246:247], v[168:169]
	v_lshlrev_b32_e32 v234, 16, v109
	v_cvt_pk_bf16_f32 v168, v162, v163
	v_lshlrev_b32_e32 v162, 16, v105
	v_and_b32_e32 v163, 0xffff0000, v105
	v_and_b32_e32 v235, 0xffff0000, v109
	v_pk_add_f32 v[234:235], v[234:235], v[162:163] neg_lo:[0,1] neg_hi:[0,1]
	s_nop 0
	v_pk_fma_f32 v[162:163], v[234:235], v[248:249], v[162:163]
	s_nop 0
	v_cvt_pk_bf16_f32 v169, v162, v163
	ds_write_b128 v213, v[166:169] offset:50688
	ds_write_b128 v214, v[110:113] offset:13824
	s_cbranch_scc1 .LBB0_683
	global_load_dwordx4 v[246:249], v[194:195], off offset:256
	global_load_dwordx4 v[250:253], v[194:195], off offset:240
	s_cmp_eq_u64 s[88:89], exec
	s_cbranch_scc1 .Lgf_3
	global_load_dwordx4 v[66:69], v200, s[84:85] offset:384
	global_load_dwordx4 v[70:73], v186, s[86:87] offset:384
	global_load_dwordx4 v[74:77], v210, s[86:87] offset:-128
	global_load_dwordx4 v[78:81], v208, s[84:85] offset:384
	global_load_dwordx4 v[82:85], v188, s[86:87] offset:384
	s_and_saveexec_b64 s[2:3], s[0:1]
	s_cbranch_execz .LBB0_678
	global_load_dwordx4 v[86:89], v206, s[86:87] offset:-128

.LBB0_683:
	ds_read_b128 v[162:165], v233 offset:18432
	ds_read_b128 v[166:169], v232
	ds_read_b128 v[234:237], v233 offset:23040
	s_cmp_gt_u32 s14, 13
	s_cselect_b64 s[2:3], -1, 0
	s_and_b64 vcc, exec, s[2:3]
	s_waitcnt lgkmcnt(1)
	v_mfma_f32_32x32x16_bf16 v[50:65], v[162:165], v[166:169], v[50:65]
	s_waitcnt lgkmcnt(0)
	v_mfma_f32_32x32x16_bf16 v[34:49], v[234:237], v[166:169], v[34:49]
	ds_read_b128 v[166:169], v232 offset:4608
	s_waitcnt lgkmcnt(0)
	v_mfma_f32_32x32x16_bf16 v[18:33], v[162:165], v[166:169], v[18:33]
	v_mfma_f32_32x32x16_bf16 v[2:17], v[234:237], v[166:169], v[2:17]
	ds_read_b128 v[162:165], v233 offset:18464
	ds_read_b128 v[166:169], v232 offset:32
	ds_read_b128 v[234:237], v233 offset:23072
	s_waitcnt lgkmcnt(1)
	v_mfma_f32_32x32x16_bf16 v[50:65], v[162:165], v[166:169], v[50:65]
	s_waitcnt lgkmcnt(0)
	v_mfma_f32_32x32x16_bf16 v[34:49], v[234:237], v[166:169], v[34:49]
	ds_read_b128 v[166:169], v232 offset:4640
	s_waitcnt lgkmcnt(0)
	v_mfma_f32_32x32x16_bf16 v[18:33], v[162:165], v[166:169], v[18:33]
	v_mfma_f32_32x32x16_bf16 v[2:17], v[234:237], v[166:169], v[2:17]
	ds_read_b128 v[162:165], v233 offset:18496
	ds_read_b128 v[166:169], v232 offset:64
	ds_read_b128 v[234:237], v233 offset:23104
	s_waitcnt lgkmcnt(1)
	v_mfma_f32_32x32x16_bf16 v[50:65], v[162:165], v[166:169], v[50:65]
	s_waitcnt lgkmcnt(0)
	v_mfma_f32_32x32x16_bf16 v[34:49], v[234:237], v[166:169], v[34:49]
	ds_read_b128 v[166:169], v232 offset:4672
	s_waitcnt lgkmcnt(0)
	v_mfma_f32_32x32x16_bf16 v[18:33], v[162:165], v[166:169], v[18:33]
	v_mfma_f32_32x32x16_bf16 v[2:17], v[234:237], v[166:169], v[2:17]
	ds_read_b128 v[162:165], v233 offset:18528
	ds_read_b128 v[166:169], v232 offset:96
	ds_read_b128 v[234:237], v233 offset:23136
	s_waitcnt lgkmcnt(1)
	v_mfma_f32_32x32x16_bf16 v[50:65], v[162:165], v[166:169], v[50:65]
	s_waitcnt lgkmcnt(0)
	v_mfma_f32_32x32x16_bf16 v[34:49], v[234:237], v[166:169], v[34:49]
	ds_read_b128 v[166:169], v232 offset:4704
	s_waitcnt lgkmcnt(0)
	s_barrier
	v_mfma_f32_32x32x16_bf16 v[18:33], v[162:165], v[166:169], v[18:33]
	v_mfma_f32_32x32x16_bf16 v[2:17], v[234:237], v[166:169], v[2:17]
	s_cbranch_vccnz .LBB0_674
	s_waitcnt vmcnt(8)
	v_lshlrev_b32_e32 v234, 16, v114
	v_and_b32_e32 v235, 0xffff0000, v114
	v_lshlrev_b32_e32 v236, 16, v118
	v_and_b32_e32 v237, 0xffff0000, v118
	v_pk_add_f32 v[236:237], v[236:237], v[234:235] neg_lo:[0,1] neg_hi:[0,1]
	v_lshlrev_b32_e32 v238, 16, v119
	v_and_b32_e32 v239, 0xffff0000, v119
	v_lshlrev_b32_e32 v240, 16, v121
	v_and_b32_e32 v241, 0xffff0000, v121
	s_cmp_gt_u32 s14, 11
	v_pk_fma_f32 v[234:235], v[236:237], v[250:251], v[234:235]
	v_lshlrev_b32_e32 v236, 16, v115
	v_and_b32_e32 v237, 0xffff0000, v115
	v_pk_add_f32 v[238:239], v[238:239], v[236:237] neg_lo:[0,1] neg_hi:[0,1]
	v_cvt_pk_bf16_f32 v234, v234, v235
	v_pk_fma_f32 v[236:237], v[238:239], v[252:253], v[236:237]
	v_lshlrev_b32_e32 v238, 16, v120
	v_cvt_pk_bf16_f32 v235, v236, v237
	v_lshlrev_b32_e32 v236, 16, v116
	v_and_b32_e32 v237, 0xffff0000, v116
	v_and_b32_e32 v239, 0xffff0000, v120
	v_pk_add_f32 v[238:239], v[238:239], v[236:237] neg_lo:[0,1] neg_hi:[0,1]
	s_nop 0
	v_pk_fma_f32 v[236:237], v[238:239], v[246:247], v[236:237]
	v_lshlrev_b32_e32 v238, 16, v117
	v_and_b32_e32 v239, 0xffff0000, v117
	v_pk_add_f32 v[240:241], v[240:241], v[238:239] neg_lo:[0,1] neg_hi:[0,1]
	v_cvt_pk_bf16_f32 v236, v236, v237
	v_pk_fma_f32 v[238:239], v[240:241], v[248:249], v[238:239]
	v_lshlrev_b32_e32 v240, 16, v133
	v_cvt_pk_bf16_f32 v237, v238, v239
	ds_write_b128 v213, v[234:237]
	ds_write_b128 v213, v[122:125] offset:18432
	v_lshlrev_b32_e32 v234, 16, v126
	v_and_b32_e32 v235, 0xffff0000, v126
	v_lshlrev_b32_e32 v236, 16, v130
	v_and_b32_e32 v237, 0xffff0000, v130
	v_pk_add_f32 v[236:237], v[236:237], v[234:235] neg_lo:[0,1] neg_hi:[0,1]
	v_lshlrev_b32_e32 v238, 16, v131
	v_pk_fma_f32 v[234:235], v[236:237], v[250:251], v[234:235]
	v_lshlrev_b32_e32 v236, 16, v127
	v_and_b32_e32 v237, 0xffff0000, v127
	v_and_b32_e32 v239, 0xffff0000, v131
	v_pk_add_f32 v[238:239], v[238:239], v[236:237] neg_lo:[0,1] neg_hi:[0,1]
	v_cvt_pk_bf16_f32 v234, v234, v235
	v_pk_fma_f32 v[236:237], v[238:239], v[252:253], v[236:237]
	v_lshlrev_b32_e32 v238, 16, v132
	v_cvt_pk_bf16_f32 v235, v236, v237
	v_lshlrev_b32_e32 v236, 16, v128
	v_and_b32_e32 v237, 0xffff0000, v128
	v_and_b32_e32 v239, 0xffff0000, v132
	v_pk_add_f32 v[238:239], v[238:239], v[236:237] neg_lo:[0,1] neg_hi:[0,1]
	v_and_b32_e32 v241, 0xffff0000, v133
	v_pk_fma_f32 v[236:237], v[238:239], v[246:247], v[236:237]
	v_lshlrev_b32_e32 v238, 16, v129
	v_and_b32_e32 v239, 0xffff0000, v129
	v_pk_add_f32 v[240:241], v[240:241], v[238:239] neg_lo:[0,1] neg_hi:[0,1]
	v_cvt_pk_bf16_f32 v236, v236, v237
	v_pk_fma_f32 v[238:239], v[240:241], v[248:249], v[238:239]
	v_lshlrev_b32_e32 v240, 16, v149
	v_cvt_pk_bf16_f32 v237, v238, v239
	ds_write_b128 v213, v[234:237] offset:4608
	ds_write_b128 v213, v[134:137] offset:23040
	v_lshlrev_b32_e32 v234, 16, v142
	v_and_b32_e32 v235, 0xffff0000, v142
	v_lshlrev_b32_e32 v236, 16, v146
	v_and_b32_e32 v237, 0xffff0000, v146
	v_pk_add_f32 v[236:237], v[236:237], v[234:235] neg_lo:[0,1] neg_hi:[0,1]
	v_lshlrev_b32_e32 v238, 16, v147
	v_pk_fma_f32 v[234:235], v[236:237], v[250:251], v[234:235]
	v_lshlrev_b32_e32 v236, 16, v143
	v_and_b32_e32 v237, 0xffff0000, v143
	v_and_b32_e32 v239, 0xffff0000, v147
	v_pk_add_f32 v[238:239], v[238:239], v[236:237] neg_lo:[0,1] neg_hi:[0,1]
	v_cvt_pk_bf16_f32 v234, v234, v235
	v_pk_fma_f32 v[236:237], v[238:239], v[252:253], v[236:237]
	v_lshlrev_b32_e32 v238, 16, v148
	v_cvt_pk_bf16_f32 v235, v236, v237
	v_lshlrev_b32_e32 v236, 16, v144
	v_and_b32_e32 v237, 0xffff0000, v144
	v_and_b32_e32 v239, 0xffff0000, v148
	v_pk_add_f32 v[238:239], v[238:239], v[236:237] neg_lo:[0,1] neg_hi:[0,1]
	v_and_b32_e32 v241, 0xffff0000, v149
	v_pk_fma_f32 v[236:237], v[238:239], v[246:247], v[236:237]
	v_lshlrev_b32_e32 v238, 16, v145
	v_and_b32_e32 v239, 0xffff0000, v145
	v_pk_add_f32 v[240:241], v[240:241], v[238:239] neg_lo:[0,1] neg_hi:[0,1]
	v_cvt_pk_bf16_f32 v236, v236, v237
	v_pk_fma_f32 v[238:239], v[240:241], v[248:249], v[238:239]
	s_nop 0
	v_cvt_pk_bf16_f32 v237, v238, v239
	ds_write_b128 v213, v[234:237] offset:9216
	ds_write_b128 v213, v[138:141] offset:27648
	v_lshlrev_b32_e32 v234, 16, v150
	v_and_b32_e32 v235, 0xffff0000, v150
	v_lshlrev_b32_e32 v236, 16, v154
	v_and_b32_e32 v237, 0xffff0000, v154
	v_pk_add_f32 v[236:237], v[236:237], v[234:235] neg_lo:[0,1] neg_hi:[0,1]
	s_nop 0
	v_pk_fma_f32 v[166:167], v[236:237], v[250:251], v[234:235]
	v_lshlrev_b32_e32 v234, 16, v151
	v_and_b32_e32 v235, 0xffff0000, v151
	v_lshlrev_b32_e32 v236, 16, v155
	v_and_b32_e32 v237, 0xffff0000, v155
	v_pk_add_f32 v[236:237], v[236:237], v[234:235] neg_lo:[0,1] neg_hi:[0,1]
	v_cvt_pk_bf16_f32 v166, v166, v167
	v_pk_fma_f32 v[168:169], v[236:237], v[252:253], v[234:235]
	v_lshlrev_b32_e32 v234, 16, v156
	v_cvt_pk_bf16_f32 v167, v168, v169
	v_lshlrev_b32_e32 v168, 16, v152
	v_and_b32_e32 v169, 0xffff0000, v152
	v_and_b32_e32 v235, 0xffff0000, v156
	v_pk_add_f32 v[234:235], v[234:235], v[168:169] neg_lo:[0,1] neg_hi:[0,1]
	s_nop 0
	v_pk_fma_f32 v[162:163], v[234:235], v[246:247], v[168:169]
	v_lshlrev_b32_e32 v234, 16, v157
	v_cvt_pk_bf16_f32 v168, v162, v163
	v_lshlrev_b32_e32 v162, 16, v153
	v_and_b32_e32 v163, 0xffff0000, v153
	v_and_b32_e32 v235, 0xffff0000, v157
	v_pk_add_f32 v[234:235], v[234:235], v[162:163] neg_lo:[0,1] neg_hi:[0,1]
	s_nop 0
	v_pk_fma_f32 v[162:163], v[234:235], v[248:249], v[162:163]
	s_nop 0
	v_cvt_pk_bf16_f32 v169, v162, v163
	ds_write_b128 v213, v[166:169] offset:13824
	ds_write_b128 v213, v[158:161] offset:32256
	global_load_dwordx4 v[246:249], v[194:195], off offset:512
	global_load_dwordx4 v[250:253], v[194:195], off offset:496
	s_cbranch_scc1 .Lmixpf_b_last
	s_cmp_eq_u64 s[88:89], exec
	s_cbranch_scc1 .Lgf_4
	global_load_dwordx4 v[114:117], v200, s[84:85] offset:512
	global_load_dwordx4 v[118:121], v186, s[86:87] offset:512
	global_load_dwordx4 v[122:125], v210, s[86:87]
	global_load_dwordx4 v[126:129], v208, s[84:85] offset:512
	global_load_dwordx4 v[130:133], v188, s[86:87] offset:512
	s_and_saveexec_b64 s[22:23], s[0:1]
	s_cbranch_execz .LBB0_687
	global_load_dwordx4 v[134:137], v206, s[86:87]

.Lgf_3:
	global_load_dwordx4 v[66:69], v200, s[84:85] offset:384
	global_load_dwordx4 v[70:73], v186, s[86:87] offset:384
	global_load_dwordx4 v[74:77], v210, s[86:87] offset:-128
	global_load_dwordx4 v[78:81], v208, s[84:85] offset:384
	global_load_dwordx4 v[82:85], v188, s[86:87] offset:384
	global_load_dwordx4 v[86:89], v206, s[86:87] offset:-128
	global_load_dwordx4 v[94:97], v204, s[84:85] offset:384
	global_load_dwordx4 v[98:101], v190, s[86:87] offset:384
	global_load_dwordx4 v[90:93], v202, s[86:87] offset:-128
	global_load_dwordx4 v[102:105], v198, s[84:85] offset:384
	global_load_dwordx4 v[106:109], v192, s[86:87] offset:384
	global_load_dwordx4 v[110:113], v196, s[86:87] offset:-128
	s_branch .LBB0_683
.Lgf_4:
	global_load_dwordx4 v[114:117], v200, s[84:85] offset:512
	global_load_dwordx4 v[118:121], v186, s[86:87] offset:512
	global_load_dwordx4 v[122:125], v210, s[86:87]
	global_load_dwordx4 v[126:129], v208, s[84:85] offset:512
	global_load_dwordx4 v[130:133], v188, s[86:87] offset:512
	global_load_dwordx4 v[134:137], v206, s[86:87]
	global_load_dwordx4 v[142:145], v204, s[84:85] offset:512
	global_load_dwordx4 v[146:149], v190, s[86:87] offset:512
	global_load_dwordx4 v[138:141], v202, s[86:87]
	global_load_dwordx4 v[150:153], v198, s[84:85] offset:512
	global_load_dwordx4 v[154:157], v192, s[86:87] offset:512
	global_load_dwordx4 v[158:161], v196, s[86:87]
	s_branch .LBB0_674

.LBB0_1721:
	s_or_b64 exec, exec, s[20:21]
	v_add_u32_e32 v4, s35, v158
	v_ashrrev_i32_e32 v5, 31, v4
	v_lshlrev_b64 v[4:5], 11, v[4:5]
	v_lshl_add_u64 v[140:141], s[82:83], 0, v[4:5]
	v_add_u32_e32 v4, s35, v159
	v_ashrrev_i32_e32 v5, 31, v4
	v_lshlrev_b64 v[4:5], 11, v[4:5]
	v_lshl_add_u64 v[144:145], s[82:83], 0, v[4:5]
	v_add_u32_e32 v4, s35, v160
	v_ashrrev_i32_e32 v5, 31, v4
	v_lshlrev_b64 v[4:5], 11, v[4:5]
	v_lshl_add_u64 v[148:149], s[82:83], 0, v[4:5]
	v_add_u32_e32 v4, s35, v1
	v_ashrrev_i32_e32 v5, 31, v4
	v_lshlrev_b64 v[4:5], 11, v[4:5]
	v_lshl_add_u64 v[138:139], s[82:83], 0, v[48:49]
	v_lshl_add_u64 v[142:143], s[82:83], 0, v[42:43]
	v_lshl_add_u64 v[146:147], s[82:83], 0, v[36:37]
	v_lshl_add_u64 v[150:151], s[82:83], 0, v[34:35]
	v_lshl_add_u64 v[152:153], s[82:83], 0, v[4:5]
	s_mov_b32 s37, 0
	v_mov_b32_e32 v3, v2
	v_mov_b32_e32 v4, v2
	v_mov_b32_e32 v5, v2
	v_mov_b32_e32 v6, v2
	v_mov_b32_e32 v7, v2
	v_mov_b32_e32 v8, v2
	v_mov_b32_e32 v9, v2
	v_mov_b32_e32 v10, v2
	v_mov_b32_e32 v11, v2
	v_mov_b32_e32 v12, v2
	v_mov_b32_e32 v13, v2
	v_mov_b32_e32 v14, v2
	v_mov_b32_e32 v15, v2
	v_mov_b32_e32 v16, v2
	v_mov_b32_e32 v17, v2
	v_mov_b32_e32 v18, v2
	v_mov_b32_e32 v19, v2
	v_mov_b32_e32 v20, v2
	v_mov_b32_e32 v21, v2
	v_mov_b32_e32 v22, v2
	v_mov_b32_e32 v23, v2
	v_mov_b32_e32 v24, v2
	v_mov_b32_e32 v25, v2
	v_mov_b32_e32 v26, v2
	v_mov_b32_e32 v27, v2
	v_mov_b32_e32 v28, v2
	v_mov_b32_e32 v29, v2
	v_mov_b32_e32 v30, v2
	v_mov_b32_e32 v31, v2
	v_mov_b32_e32 v32, v2
	v_mov_b32_e32 v33, v2
	v_mov_b32_e32 v34, v2
	v_mov_b32_e32 v35, v2
	v_mov_b32_e32 v36, v2
	v_mov_b32_e32 v37, v2
	v_mov_b32_e32 v38, v2
	v_mov_b32_e32 v39, v2
	v_mov_b32_e32 v40, v2
	v_mov_b32_e32 v41, v2
	v_mov_b32_e32 v42, v2
	v_mov_b32_e32 v43, v2
	v_mov_b32_e32 v44, v2
	v_mov_b32_e32 v45, v2
	v_mov_b32_e32 v46, v2
	v_mov_b32_e32 v47, v2
	v_mov_b32_e32 v48, v2
	v_mov_b32_e32 v49, v2
	v_mov_b32_e32 v50, v2
	v_mov_b32_e32 v51, v2
	v_mov_b32_e32 v52, v2
	v_mov_b32_e32 v53, v2
	v_mov_b32_e32 v54, v2
	v_mov_b32_e32 v55, v2
	v_mov_b32_e32 v56, v2
	v_mov_b32_e32 v57, v2
	v_mov_b32_e32 v58, v2
	v_mov_b32_e32 v59, v2
	v_mov_b32_e32 v60, v2
	v_mov_b32_e32 v61, v2
	v_mov_b32_e32 v62, v2
	v_mov_b32_e32 v63, v2
	v_mov_b32_e32 v64, v2
	v_mov_b32_e32 v65, v2
	s_waitcnt lgkmcnt(0)
	s_barrier
	ds_read_b128 v[192:195], v161 offset:0
	ds_read_b128 v[196:199], v162 offset:18432
	ds_read_b128 v[200:203], v162 offset:23040
	ds_read_b128 v[204:207], v161 offset:4608
	ds_read_b128 v[208:211], v161 offset:32
	ds_read_b128 v[212:215], v162 offset:18464
	ds_read_b128 v[216:219], v162 offset:23072
	ds_read_b128 v[220:223], v161 offset:4640
	v_subrev_u32_e32 v152, s82, v152
	v_add_u32_e32 v152, v152, v136
	v_subrev_u32_e32 v150, s82, v150
	v_add_u32_e32 v150, v150, v136
	v_subrev_u32_e32 v148, s82, v148
	v_add_u32_e32 v148, v148, v136
	v_subrev_u32_e32 v146, s82, v146
	v_add_u32_e32 v146, v146, v136
	v_subrev_u32_e32 v144, s82, v144
	v_add_u32_e32 v144, v144, v136
	v_subrev_u32_e32 v142, s82, v142
	v_add_u32_e32 v142, v142, v136
	v_subrev_u32_e32 v140, s82, v140
	v_add_u32_e32 v140, v140, v136
	v_subrev_u32_e32 v138, s82, v138
	v_add_u32_e32 v138, v138, v136
	s_add_u32 s84, s82, 0xa380000
	s_addc_u32 s85, s83, 0
	s_add_u32 s86, s82, 0x89c0000
	s_addc_u32 s87, s83, 0
	s_mov_b64 s[88:89], s[4:5]
	s_and_b64 s[88:89], s[88:89], s[6:7]
	s_and_b64 s[88:89], s[88:89], s[8:9]
	s_and_b64 s[88:89], s[88:89], s[10:11]
	s_branch .LBB0_1724

.LBB0_1724:
	s_cmp_gt_u32 s37, 12
	s_waitcnt vmcnt(3)
	ds_write_b128 v154, v[66:69] offset:36864
	ds_write_b128 v154, v[70:73] offset:55296
	s_waitcnt vmcnt(2)
	ds_write_b128 v154, v[78:81] offset:41472
	ds_write_b128 v154, v[74:77] offset:59904
	s_waitcnt vmcnt(1)
	ds_write_b128 v154, v[82:85] offset:46080
	ds_write_b128 v154, v[90:93] offset:64512
	s_waitcnt vmcnt(0)
	ds_write_b128 v154, v[102:105] offset:50688
	ds_write_b128 v156, v[106:109] offset:13824
	s_cbranch_scc1 .LBB0_1734
	s_cmp_eq_u64 s[88:89], exec
	s_cbranch_scc1 .Lgf_5
	global_load_dwordx4 v[66:69], v152, s[84:85] offset:384
	s_and_saveexec_b64 s[20:21], s[4:5]
	s_cbranch_execz .LBB0_1727
	global_load_dwordx4 v[70:73], v150, s[86:87] offset:384

.LBB0_1734:
	s_cmp_gt_u32 s37, 13
	s_cselect_b64 s[20:21], -1, 0
	s_and_b64 vcc, exec, s[20:21]
	s_waitcnt lgkmcnt(4)
	v_mfma_f32_32x32x16_bf16 v[50:65], v[192:195], v[196:199], v[50:65]
	v_mfma_f32_32x32x16_bf16 v[34:49], v[192:195], v[200:203], v[34:49]
	v_mfma_f32_32x32x16_bf16 v[18:33], v[204:207], v[196:199], v[18:33]
	v_mfma_f32_32x32x16_bf16 v[2:17], v[204:207], v[200:203], v[2:17]
	ds_read_b128 v[164:167], v161 offset:64
	ds_read_b128 v[168:171], v162 offset:18496
	ds_read_b128 v[172:175], v162 offset:23104
	ds_read_b128 v[176:179], v161 offset:4672
	s_waitcnt lgkmcnt(4)
	v_mfma_f32_32x32x16_bf16 v[50:65], v[208:211], v[212:215], v[50:65]
	v_mfma_f32_32x32x16_bf16 v[34:49], v[208:211], v[216:219], v[34:49]
	v_mfma_f32_32x32x16_bf16 v[18:33], v[220:223], v[212:215], v[18:33]
	v_mfma_f32_32x32x16_bf16 v[2:17], v[220:223], v[216:219], v[2:17]
	ds_read_b128 v[180:183], v161 offset:96
	ds_read_b128 v[184:187], v162 offset:18528
	ds_read_b128 v[188:191], v162 offset:23136
	ds_read_b128 v[224:227], v161 offset:4704
	s_waitcnt lgkmcnt(4)
	v_mfma_f32_32x32x16_bf16 v[50:65], v[164:167], v[168:171], v[50:65]
	v_mfma_f32_32x32x16_bf16 v[34:49], v[164:167], v[172:175], v[34:49]
	s_waitcnt lgkmcnt(0)
	s_barrier
	ds_read_b128 v[192:195], v161 offset:36864
	ds_read_b128 v[196:199], v162 offset:55296
	ds_read_b128 v[200:203], v162 offset:59904
	ds_read_b128 v[204:207], v161 offset:41472
	ds_read_b128 v[208:211], v161 offset:36896
	ds_read_b128 v[212:215], v162 offset:55328
	ds_read_b128 v[216:219], v162 offset:59936
	ds_read_b128 v[220:223], v161 offset:41504
	v_mfma_f32_32x32x16_bf16 v[18:33], v[176:179], v[168:171], v[18:33]
	v_mfma_f32_32x32x16_bf16 v[2:17], v[176:179], v[172:175], v[2:17]
	v_mfma_f32_32x32x16_bf16 v[50:65], v[180:183], v[184:187], v[50:65]
	v_mfma_f32_32x32x16_bf16 v[34:49], v[180:183], v[188:191], v[34:49]
	v_mfma_f32_32x32x16_bf16 v[18:33], v[224:227], v[184:187], v[18:33]
	v_mfma_f32_32x32x16_bf16 v[2:17], v[224:227], v[188:191], v[2:17]
	s_cbranch_vccnz .LBB0_1723
	s_cmp_gt_u32 s37, 11
	s_waitcnt vmcnt(3)
	ds_write_b128 v154, v[86:89]
	ds_write_b128 v154, v[94:97] offset:18432
	s_waitcnt vmcnt(2)
	ds_write_b128 v154, v[110:113] offset:4608
	ds_write_b128 v154, v[98:101] offset:23040
	s_waitcnt vmcnt(1)
	ds_write_b128 v154, v[114:117] offset:9216
	ds_write_b128 v154, v[118:121] offset:27648
	s_waitcnt vmcnt(0)
	ds_write_b128 v154, v[122:125] offset:13824
	ds_write_b128 v154, v[126:129] offset:32256
	s_cbranch_scc1 .LBB0_1723
	s_cmp_eq_u64 s[88:89], exec
	s_cbranch_scc1 .Lgf_6
	global_load_dwordx4 v[86:89], v152, s[84:85] offset:512
	s_and_saveexec_b64 s[22:23], s[4:5]
	s_cbranch_execz .LBB0_1738
	global_load_dwordx4 v[94:97], v150, s[86:87] offset:512

.Lgf_5:
	global_load_dwordx4 v[66:69], v152, s[84:85] offset:384
	global_load_dwordx4 v[70:73], v150, s[86:87] offset:384
	global_load_dwordx4 v[78:81], v148, s[84:85] offset:384
	global_load_dwordx4 v[74:77], v146, s[86:87] offset:384
	global_load_dwordx4 v[82:85], v144, s[84:85] offset:384
	global_load_dwordx4 v[90:93], v142, s[86:87] offset:384
	global_load_dwordx4 v[102:105], v140, s[84:85] offset:384
	global_load_dwordx4 v[106:109], v138, s[86:87] offset:384
	s_branch .LBB0_1734
.Lgf_6:
	global_load_dwordx4 v[86:89], v152, s[84:85] offset:512
	global_load_dwordx4 v[94:97], v150, s[86:87] offset:512
	global_load_dwordx4 v[110:113], v148, s[84:85] offset:512
	global_load_dwordx4 v[98:101], v146, s[86:87] offset:512
	global_load_dwordx4 v[114:117], v144, s[84:85] offset:512
	global_load_dwordx4 v[118:121], v142, s[86:87] offset:512
	global_load_dwordx4 v[122:125], v140, s[84:85] offset:512
	global_load_dwordx4 v[126:129], v138, s[86:87] offset:512
	s_branch .LBB0_1723

.LBB0_1920:
	s_or_b64 exec, exec, s[2:3]
	v_add_u32_e32 v2, s33, v194
	v_ashrrev_i32_e32 v3, 31, v2
	v_lshlrev_b64 v[2:3], 11, v[2:3]
	v_lshl_add_u64 v[168:169], s[82:83], 0, v[2:3]
	v_add_u32_e32 v2, s33, v195
	v_ashrrev_i32_e32 v3, 31, v2
	v_lshlrev_b64 v[2:3], 11, v[2:3]
	v_lshl_add_u64 v[172:173], s[82:83], 0, v[2:3]
	v_add_u32_e32 v2, s33, v196
	v_ashrrev_i32_e32 v3, 31, v2
	v_lshlrev_b64 v[2:3], 11, v[2:3]
	v_lshl_add_u64 v[176:177], s[82:83], 0, v[2:3]
	v_add_u32_e32 v2, s33, v1
	v_ashrrev_i32_e32 v3, 31, v2
	v_lshlrev_b64 v[2:3], 11, v[2:3]
	v_lshl_add_u64 v[166:167], s[82:83], 0, v[48:49]
	v_lshl_add_u64 v[170:171], s[82:83], 0, v[42:43]
	v_lshl_add_u64 v[174:175], s[82:83], 0, v[36:37]
	v_lshl_add_u64 v[178:179], s[82:83], 0, v[34:35]
	v_lshl_add_u64 v[180:181], s[82:83], 0, v[2:3]
	s_mov_b32 s35, 0
	v_mov_b32_e32 v51, v50
	v_mov_b32_e32 v52, v50
	v_mov_b32_e32 v53, v50
	v_mov_b32_e32 v54, v50
	v_mov_b32_e32 v55, v50
	v_mov_b32_e32 v56, v50
	v_mov_b32_e32 v57, v50
	v_mov_b32_e32 v58, v50
	v_mov_b32_e32 v59, v50
	v_mov_b32_e32 v60, v50
	v_mov_b32_e32 v61, v50
	v_mov_b32_e32 v62, v50
	v_mov_b32_e32 v63, v50
	v_mov_b32_e32 v64, v50
	v_mov_b32_e32 v65, v50
	v_mov_b32_e32 v34, v50
	v_mov_b32_e32 v35, v50
	v_mov_b32_e32 v36, v50
	v_mov_b32_e32 v37, v50
	v_mov_b32_e32 v38, v50
	v_mov_b32_e32 v39, v50
	v_mov_b32_e32 v40, v50
	v_mov_b32_e32 v41, v50
	v_mov_b32_e32 v42, v50
	v_mov_b32_e32 v43, v50
	v_mov_b32_e32 v44, v50
	v_mov_b32_e32 v45, v50
	v_mov_b32_e32 v46, v50
	v_mov_b32_e32 v47, v50
	v_mov_b32_e32 v48, v50
	v_mov_b32_e32 v49, v50
	v_mov_b32_e32 v18, v50
	v_mov_b32_e32 v19, v50
	v_mov_b32_e32 v20, v50
	v_mov_b32_e32 v21, v50
	v_mov_b32_e32 v22, v50
	v_mov_b32_e32 v23, v50
	v_mov_b32_e32 v24, v50
	v_mov_b32_e32 v25, v50
	v_mov_b32_e32 v26, v50
	v_mov_b32_e32 v27, v50
	v_mov_b32_e32 v28, v50
	v_mov_b32_e32 v29, v50
	v_mov_b32_e32 v30, v50
	v_mov_b32_e32 v31, v50
	v_mov_b32_e32 v32, v50
	v_mov_b32_e32 v33, v50
	v_mov_b32_e32 v2, v50
	v_mov_b32_e32 v3, v50
	v_mov_b32_e32 v4, v50
	v_mov_b32_e32 v5, v50
	v_mov_b32_e32 v6, v50
	v_mov_b32_e32 v7, v50
	v_mov_b32_e32 v8, v50
	v_mov_b32_e32 v9, v50
	v_mov_b32_e32 v10, v50
	v_mov_b32_e32 v11, v50
	v_mov_b32_e32 v12, v50
	v_mov_b32_e32 v13, v50
	v_mov_b32_e32 v14, v50
	v_mov_b32_e32 v15, v50
	v_mov_b32_e32 v16, v50
	v_mov_b32_e32 v17, v50
	s_waitcnt lgkmcnt(0)
	s_barrier
	ds_read_b128 v[206:209], v203 offset:0
	ds_read_b128 v[210:213], v204 offset:18432
	ds_read_b128 v[214:217], v204 offset:23040
	ds_read_b128 v[218:221], v203 offset:4608
	ds_read_b128 v[222:225], v203 offset:32
	ds_read_b128 v[226:229], v204 offset:18464
	ds_read_b128 v[230:233], v204 offset:23072
	ds_read_b128 v[234:237], v203 offset:4640
	v_subrev_u32_e32 v180, s82, v180
	v_add_u32_e32 v180, v180, v138
	v_subrev_u32_e32 v178, s82, v178
	v_add_u32_e32 v178, v178, v138
	v_subrev_u32_e32 v176, s82, v176
	v_add_u32_e32 v176, v176, v138
	v_subrev_u32_e32 v174, s82, v174
	v_add_u32_e32 v174, v174, v138
	v_subrev_u32_e32 v172, s82, v172
	v_add_u32_e32 v172, v172, v138
	v_subrev_u32_e32 v170, s82, v170
	v_add_u32_e32 v170, v170, v138
	v_subrev_u32_e32 v168, s82, v168
	v_add_u32_e32 v168, v168, v138
	v_subrev_u32_e32 v166, s82, v166
	v_add_u32_e32 v166, v166, v138
	s_add_u32 s84, s82, 0xc4c0000
	s_addc_u32 s85, s83, 0
	s_add_u32 s86, s82, 0x99d0000
	s_addc_u32 s87, s83, 0
	s_mov_b64 s[88:89], s[12:13]
	s_and_b64 s[88:89], s[88:89], s[14:15]
	s_and_b64 s[88:89], s[88:89], s[16:17]
	s_and_b64 s[88:89], s[88:89], s[18:19]
	s_branch .LBB0_1923

.LBB0_1923:
	s_cmp_gt_u32 s35, 12
	s_waitcnt vmcnt(3)
	ds_write_b128 v137, v[66:69] offset:36864
	ds_write_b128 v137, v[70:73] offset:55296
	s_waitcnt vmcnt(2)
	ds_write_b128 v137, v[78:81] offset:41472
	ds_write_b128 v137, v[74:77] offset:59904
	s_waitcnt vmcnt(1)
	ds_write_b128 v137, v[82:85] offset:46080
	ds_write_b128 v137, v[90:93] offset:64512
	s_waitcnt vmcnt(0)
	ds_write_b128 v137, v[102:105] offset:50688
	ds_write_b128 v183, v[106:109] offset:13824
	s_cbranch_scc1 .LBB0_1933
	s_cmp_eq_u64 s[88:89], exec
	s_cbranch_scc1 .Lgf_7
	global_load_dwordx4 v[66:69], v180, s[84:85] offset:384
	s_and_saveexec_b64 s[2:3], s[12:13]
	s_cbranch_execz .LBB0_1926
	global_load_dwordx4 v[70:73], v178, s[86:87] offset:384

.LBB0_1933:
	s_cmp_gt_u32 s35, 13
	s_cselect_b64 s[2:3], -1, 0
	s_and_b64 vcc, exec, s[2:3]
	s_waitcnt lgkmcnt(4)
	v_mfma_f32_32x32x16_bf16 v[50:65], v[206:209], v[210:213], v[50:65]
	v_mfma_f32_32x32x16_bf16 v[34:49], v[206:209], v[214:217], v[34:49]
	v_mfma_f32_32x32x16_bf16 v[18:33], v[218:221], v[210:213], v[18:33]
	v_mfma_f32_32x32x16_bf16 v[2:17], v[218:221], v[214:217], v[2:17]
	ds_read_b128 v[206:209], v203 offset:64
	ds_read_b128 v[210:213], v204 offset:18496
	ds_read_b128 v[214:217], v204 offset:23104
	ds_read_b128 v[218:221], v203 offset:4672
	s_waitcnt lgkmcnt(4)
	v_mfma_f32_32x32x16_bf16 v[50:65], v[222:225], v[226:229], v[50:65]
	v_mfma_f32_32x32x16_bf16 v[34:49], v[222:225], v[230:233], v[34:49]
	v_mfma_f32_32x32x16_bf16 v[18:33], v[234:237], v[226:229], v[18:33]
	v_mfma_f32_32x32x16_bf16 v[2:17], v[234:237], v[230:233], v[2:17]
	ds_read_b128 v[222:225], v203 offset:96
	ds_read_b128 v[226:229], v204 offset:18528
	ds_read_b128 v[230:233], v204 offset:23136
	ds_read_b128 v[234:237], v203 offset:4704
	s_waitcnt lgkmcnt(4)
	v_mfma_f32_32x32x16_bf16 v[50:65], v[206:209], v[210:213], v[50:65]
	v_mfma_f32_32x32x16_bf16 v[34:49], v[206:209], v[214:217], v[34:49]
	s_waitcnt lgkmcnt(0)
	s_barrier
	v_mfma_f32_32x32x16_bf16 v[18:33], v[218:221], v[210:213], v[18:33]
	v_mfma_f32_32x32x16_bf16 v[2:17], v[218:221], v[214:217], v[2:17]
	ds_read_b128 v[206:209], v203 offset:36864
	ds_read_b128 v[210:213], v204 offset:55296
	ds_read_b128 v[214:217], v204 offset:59904
	ds_read_b128 v[218:221], v203 offset:41472
	v_mfma_f32_32x32x16_bf16 v[50:65], v[222:225], v[226:229], v[50:65]
	v_mfma_f32_32x32x16_bf16 v[34:49], v[222:225], v[230:233], v[34:49]
	v_mfma_f32_32x32x16_bf16 v[18:33], v[234:237], v[226:229], v[18:33]
	v_mfma_f32_32x32x16_bf16 v[2:17], v[234:237], v[230:233], v[2:17]
	ds_read_b128 v[222:225], v203 offset:36896
	ds_read_b128 v[226:229], v204 offset:55328
	ds_read_b128 v[230:233], v204 offset:59936
	ds_read_b128 v[234:237], v203 offset:41504
	s_cbranch_vccnz .LBB0_1922
	s_cmp_gt_u32 s35, 11
	s_waitcnt vmcnt(3)
	ds_write_b128 v137, v[86:89]
	ds_write_b128 v137, v[94:97] offset:18432
	s_waitcnt vmcnt(2)
	ds_write_b128 v137, v[110:113] offset:4608
	ds_write_b128 v137, v[98:101] offset:23040
	s_waitcnt vmcnt(1)
	ds_write_b128 v137, v[114:117] offset:9216
	ds_write_b128 v137, v[118:121] offset:27648
	s_waitcnt vmcnt(0)
	ds_write_b128 v137, v[122:125] offset:13824
	ds_write_b128 v137, v[126:129] offset:32256
	s_cbranch_scc1 .LBB0_1922
	s_cmp_eq_u64 s[88:89], exec
	s_cbranch_scc1 .Lgf_8
	global_load_dwordx4 v[86:89], v180, s[84:85] offset:512
	s_and_saveexec_b64 s[36:37], s[12:13]
	s_cbranch_execz .LBB0_1937
	global_load_dwordx4 v[94:97], v178, s[86:87] offset:512

.Lgf_7:
	global_load_dwordx4 v[66:69], v180, s[84:85] offset:384
	global_load_dwordx4 v[70:73], v178, s[86:87] offset:384
	global_load_dwordx4 v[78:81], v176, s[84:85] offset:384
	global_load_dwordx4 v[74:77], v174, s[86:87] offset:384
	global_load_dwordx4 v[82:85], v172, s[84:85] offset:384
	global_load_dwordx4 v[90:93], v170, s[86:87] offset:384
	global_load_dwordx4 v[102:105], v168, s[84:85] offset:384
	global_load_dwordx4 v[106:109], v166, s[86:87] offset:384
	s_branch .LBB0_1933
.Lgf_8:
	global_load_dwordx4 v[86:89], v180, s[84:85] offset:512
	global_load_dwordx4 v[94:97], v178, s[86:87] offset:512
	global_load_dwordx4 v[110:113], v176, s[84:85] offset:512
	global_load_dwordx4 v[98:101], v174, s[86:87] offset:512
	global_load_dwordx4 v[114:117], v172, s[84:85] offset:512
	global_load_dwordx4 v[118:121], v170, s[86:87] offset:512
	global_load_dwordx4 v[122:125], v168, s[84:85] offset:512
	global_load_dwordx4 v[126:129], v166, s[86:87] offset:512
	s_branch .LBB0_1922

.LBB0_2250:
	s_or_b64 exec, exec, s[2:3]
	v_add_u32_e32 v4, s27, v180
	v_ashrrev_i32_e32 v5, 31, v4
	v_lshlrev_b64 v[4:5], 11, v[4:5]
	v_lshl_add_u64 v[146:147], s[82:83], 0, v[4:5]
	v_add_u32_e32 v4, s27, v181
	v_ashrrev_i32_e32 v5, 31, v4
	v_lshlrev_b64 v[4:5], 11, v[4:5]
	v_lshl_add_u64 v[154:155], s[82:83], 0, v[4:5]
	v_add_u32_e32 v4, s26, v1
	v_ashrrev_i32_e32 v5, 31, v4
	v_lshlrev_b64 v[4:5], 11, v[4:5]
	v_lshl_add_u64 v[156:157], s[82:83], 0, v[4:5]
	v_add_u32_e32 v4, s27, v1
	v_ashrrev_i32_e32 v5, 31, v4
	v_lshlrev_b64 v[4:5], 11, v[4:5]
	v_lshl_add_u64 v[144:145], s[82:83], 0, v[40:41]
	v_lshl_add_u64 v[148:149], s[82:83], 0, v[38:39]
	v_lshl_add_u64 v[150:151], s[82:83], 0, v[36:37]
	v_lshl_add_u64 v[152:153], s[82:83], 0, v[34:35]
	v_lshl_add_u64 v[158:159], s[82:83], 0, v[4:5]
	s_mov_b32 s13, 0
	v_mov_b32_e32 v3, v2
	v_mov_b32_e32 v4, v2
	v_mov_b32_e32 v5, v2
	v_mov_b32_e32 v6, v2
	v_mov_b32_e32 v7, v2
	v_mov_b32_e32 v8, v2
	v_mov_b32_e32 v9, v2
	v_mov_b32_e32 v10, v2
	v_mov_b32_e32 v11, v2
	v_mov_b32_e32 v12, v2
	v_mov_b32_e32 v13, v2
	v_mov_b32_e32 v14, v2
	v_mov_b32_e32 v15, v2
	v_mov_b32_e32 v16, v2
	v_mov_b32_e32 v17, v2
	v_mov_b32_e32 v18, v2
	v_mov_b32_e32 v19, v2
	v_mov_b32_e32 v20, v2
	v_mov_b32_e32 v21, v2
	v_mov_b32_e32 v22, v2
	v_mov_b32_e32 v23, v2
	v_mov_b32_e32 v24, v2
	v_mov_b32_e32 v25, v2
	v_mov_b32_e32 v26, v2
	v_mov_b32_e32 v27, v2
	v_mov_b32_e32 v28, v2
	v_mov_b32_e32 v29, v2
	v_mov_b32_e32 v30, v2
	v_mov_b32_e32 v31, v2
	v_mov_b32_e32 v32, v2
	v_mov_b32_e32 v33, v2
	v_mov_b32_e32 v34, v2
	v_mov_b32_e32 v35, v2
	v_mov_b32_e32 v36, v2
	v_mov_b32_e32 v37, v2
	v_mov_b32_e32 v38, v2
	v_mov_b32_e32 v39, v2
	v_mov_b32_e32 v40, v2
	v_mov_b32_e32 v41, v2
	v_mov_b32_e32 v42, v2
	v_mov_b32_e32 v43, v2
	v_mov_b32_e32 v44, v2
	v_mov_b32_e32 v45, v2
	v_mov_b32_e32 v46, v2
	v_mov_b32_e32 v47, v2
	v_mov_b32_e32 v48, v2
	v_mov_b32_e32 v49, v2
	v_mov_b32_e32 v50, v2
	v_mov_b32_e32 v51, v2
	v_mov_b32_e32 v52, v2
	v_mov_b32_e32 v53, v2
	v_mov_b32_e32 v54, v2
	v_mov_b32_e32 v55, v2
	v_mov_b32_e32 v56, v2
	v_mov_b32_e32 v57, v2
	v_mov_b32_e32 v58, v2
	v_mov_b32_e32 v59, v2
	v_mov_b32_e32 v60, v2
	v_mov_b32_e32 v61, v2
	v_mov_b32_e32 v62, v2
	v_mov_b32_e32 v63, v2
	v_mov_b32_e32 v64, v2
	v_mov_b32_e32 v65, v2
	s_waitcnt lgkmcnt(0)
	s_barrier
	ds_read_b128 v[212:215], v182 offset:18432
	ds_read_b128 v[216:219], v162 offset:0
	ds_read_b128 v[220:223], v182 offset:23040
	ds_read_b128 v[224:227], v162 offset:4608
	ds_read_b128 v[228:231], v182 offset:18464
	ds_read_b128 v[232:235], v162 offset:32
	ds_read_b128 v[236:239], v182 offset:23072
	ds_read_b128 v[240:243], v162 offset:4640
	v_subrev_u32_e32 v158, s82, v158
	v_add_u32_e32 v158, v158, v140
	v_subrev_u32_e32 v156, s82, v156
	v_add_u32_e32 v156, v156, v140
	v_subrev_u32_e32 v154, s82, v154
	v_add_u32_e32 v154, v154, v140
	v_subrev_u32_e32 v152, s82, v152
	v_add_u32_e32 v152, v152, v140
	v_subrev_u32_e32 v150, s82, v150
	v_add_u32_e32 v150, v150, v140
	v_subrev_u32_e32 v148, s82, v148
	v_add_u32_e32 v148, v148, v140
	v_subrev_u32_e32 v146, s82, v146
	v_add_u32_e32 v146, v146, v140
	v_subrev_u32_e32 v144, s82, v144
	v_add_u32_e32 v144, v144, v140
	s_add_u32 s84, s82, 0xa380000
	s_addc_u32 s85, s83, 0
	s_add_u32 s86, s82, 0x8bc0000
	s_addc_u32 s87, s83, 0
	s_mov_b64 s[88:89], s[6:7]
	s_and_b64 s[88:89], s[88:89], s[8:9]
	s_branch .LBB0_2253

.LBB0_2253:
	s_cmp_gt_u32 s13, 12
	s_waitcnt vmcnt(5)
	ds_write_b128 v160, v[66:69] offset:36864
	s_waitcnt vmcnt(4)
	ds_write_b128 v160, v[70:73] offset:55296
	s_waitcnt vmcnt(3)
	ds_write_b128 v160, v[74:77] offset:41472
	s_waitcnt vmcnt(2)
	ds_write_b128 v160, v[78:81] offset:59904
	s_waitcnt vmcnt(1)
	ds_write_b128 v160, v[82:85] offset:46080
	ds_write_b128 v160, v[86:89] offset:64512
	s_waitcnt vmcnt(0)
	ds_write_b128 v160, v[102:105] offset:50688
	ds_write_b128 v161, v[114:117] offset:13824
	s_cbranch_scc1 .LBB0_2259
	s_cmp_eq_u64 s[88:89], exec
	s_cbranch_scc1 .Lgf_9
	global_load_dwordx4 v[66:69], v158, s[84:85] offset:384
	global_load_dwordx4 v[70:73], v156, s[86:87] offset:384
	v_mov_b32_e32 v131, v130
	global_load_dwordx4 v[74:77], v154, s[84:85] offset:384
	global_load_dwordx4 v[78:81], v152, s[86:87] offset:384
	global_load_dwordx4 v[82:85], v150, s[84:85] offset:384
	s_and_saveexec_b64 s[2:3], s[6:7]
	s_cbranch_execz .LBB0_2256
	global_load_dwordx4 v[86:89], v148, s[86:87] offset:384

.LBB0_2259:
	s_cmp_gt_u32 s13, 13
	s_cselect_b64 s[2:3], -1, 0
	s_and_b64 vcc, exec, s[2:3]
	s_waitcnt lgkmcnt(4)
	v_mfma_f32_32x32x16_bf16 v[50:65], v[212:215], v[216:219], v[50:65]
	v_mfma_f32_32x32x16_bf16 v[34:49], v[220:223], v[216:219], v[34:49]
	v_mfma_f32_32x32x16_bf16 v[18:33], v[212:215], v[224:227], v[18:33]
	v_mfma_f32_32x32x16_bf16 v[2:17], v[220:223], v[224:227], v[2:17]
	ds_read_b128 v[184:187], v182 offset:18496
	ds_read_b128 v[188:191], v162 offset:64
	ds_read_b128 v[192:195], v182 offset:23104
	ds_read_b128 v[196:199], v162 offset:4672
	s_waitcnt lgkmcnt(4)
	v_mfma_f32_32x32x16_bf16 v[50:65], v[228:231], v[232:235], v[50:65]
	v_mfma_f32_32x32x16_bf16 v[34:49], v[236:239], v[232:235], v[34:49]
	v_mfma_f32_32x32x16_bf16 v[18:33], v[228:231], v[240:243], v[18:33]
	v_mfma_f32_32x32x16_bf16 v[2:17], v[236:239], v[240:243], v[2:17]
	ds_read_b128 v[200:203], v182 offset:18528
	ds_read_b128 v[204:207], v162 offset:96
	ds_read_b128 v[208:211], v182 offset:23136
	ds_read_b128 v[248:251], v162 offset:4704
	s_waitcnt lgkmcnt(4)
	v_mfma_f32_32x32x16_bf16 v[50:65], v[184:187], v[188:191], v[50:65]
	v_mfma_f32_32x32x16_bf16 v[34:49], v[192:195], v[188:191], v[34:49]
	s_waitcnt lgkmcnt(0)
	s_barrier
	ds_read_b128 v[212:215], v182 offset:55296
	ds_read_b128 v[216:219], v162 offset:36864
	ds_read_b128 v[220:223], v182 offset:59904
	ds_read_b128 v[224:227], v162 offset:41472
	ds_read_b128 v[228:231], v182 offset:55328
	ds_read_b128 v[232:235], v162 offset:36896
	ds_read_b128 v[236:239], v182 offset:59936
	ds_read_b128 v[240:243], v162 offset:41504
	v_mfma_f32_32x32x16_bf16 v[18:33], v[184:187], v[196:199], v[18:33]
	v_mfma_f32_32x32x16_bf16 v[2:17], v[192:195], v[196:199], v[2:17]
	v_mfma_f32_32x32x16_bf16 v[50:65], v[200:203], v[204:207], v[50:65]
	v_mfma_f32_32x32x16_bf16 v[34:49], v[208:211], v[204:207], v[34:49]
	v_mfma_f32_32x32x16_bf16 v[18:33], v[200:203], v[248:251], v[18:33]
	v_mfma_f32_32x32x16_bf16 v[2:17], v[208:211], v[248:251], v[2:17]
	s_cbranch_vccnz .LBB0_2252
	s_cmp_gt_u32 s13, 11
	s_waitcnt vmcnt(5)
	ds_write_b128 v160, v[90:93]
	s_waitcnt vmcnt(4)
	ds_write_b128 v160, v[94:97] offset:18432
	s_waitcnt vmcnt(3)
	ds_write_b128 v160, v[98:101] offset:4608
	s_waitcnt vmcnt(2)
	ds_write_b128 v160, v[106:109] offset:23040
	s_waitcnt vmcnt(1)
	ds_write_b128 v160, v[110:113] offset:9216
	ds_write_b128 v160, v[118:121] offset:27648
	s_waitcnt vmcnt(0)
	ds_write_b128 v160, v[122:125] offset:13824
	ds_write_b128 v160, v[126:129] offset:32256
	s_cbranch_scc1 .LBB0_2252
	s_cmp_eq_u64 s[88:89], exec
	s_cbranch_scc1 .Lgf_10
	global_load_dwordx4 v[90:93], v158, s[84:85] offset:512
	global_load_dwordx4 v[94:97], v156, s[86:87] offset:512
	v_mov_b32_e32 v131, v130
	global_load_dwordx4 v[98:101], v154, s[84:85] offset:512
	global_load_dwordx4 v[106:109], v152, s[86:87] offset:512
	global_load_dwordx4 v[110:113], v150, s[84:85] offset:512
	s_and_saveexec_b64 s[14:15], s[6:7]
	s_cbranch_execz .LBB0_2263
	global_load_dwordx4 v[118:121], v148, s[86:87] offset:512

.Lgf_9:
	global_load_dwordx4 v[66:69], v158, s[84:85] offset:384
	global_load_dwordx4 v[70:73], v156, s[86:87] offset:384
	global_load_dwordx4 v[74:77], v154, s[84:85] offset:384
	global_load_dwordx4 v[78:81], v152, s[86:87] offset:384
	global_load_dwordx4 v[82:85], v150, s[84:85] offset:384
	global_load_dwordx4 v[86:89], v148, s[86:87] offset:384
	global_load_dwordx4 v[102:105], v146, s[84:85] offset:384
	global_load_dwordx4 v[114:117], v144, s[86:87] offset:384
	s_branch .LBB0_2259
.Lgf_10:
	global_load_dwordx4 v[90:93], v158, s[84:85] offset:512
	global_load_dwordx4 v[94:97], v156, s[86:87] offset:512
	global_load_dwordx4 v[98:101], v154, s[84:85] offset:512
	global_load_dwordx4 v[106:109], v152, s[86:87] offset:512
	global_load_dwordx4 v[110:113], v150, s[84:85] offset:512
	global_load_dwordx4 v[118:121], v148, s[86:87] offset:512
	global_load_dwordx4 v[122:125], v146, s[84:85] offset:512
	global_load_dwordx4 v[126:129], v144, s[86:87] offset:512
	s_branch .LBB0_2252

.LBB0_2922:
	s_or_b64 exec, exec, s[20:21]
	v_add_u32_e32 v4, s35, v158
	v_ashrrev_i32_e32 v5, 31, v4
	v_lshlrev_b64 v[4:5], 12, v[4:5]
	v_lshl_add_u64 v[140:141], s[82:83], 0, v[4:5]
	v_add_u32_e32 v4, s35, v159
	v_ashrrev_i32_e32 v5, 31, v4
	v_lshlrev_b64 v[4:5], 12, v[4:5]
	v_lshl_add_u64 v[144:145], s[82:83], 0, v[4:5]
	v_add_u32_e32 v4, s35, v160
	v_ashrrev_i32_e32 v5, 31, v4
	v_lshlrev_b64 v[4:5], 12, v[4:5]
	v_lshl_add_u64 v[148:149], s[82:83], 0, v[4:5]
	v_add_u32_e32 v4, s35, v1
	v_ashrrev_i32_e32 v5, 31, v4
	v_lshlrev_b64 v[4:5], 12, v[4:5]
	v_lshl_add_u64 v[138:139], s[82:83], 0, v[48:49]
	v_lshl_add_u64 v[142:143], s[82:83], 0, v[42:43]
	v_lshl_add_u64 v[146:147], s[82:83], 0, v[36:37]
	v_lshl_add_u64 v[150:151], s[82:83], 0, v[34:35]
	v_lshl_add_u64 v[152:153], s[82:83], 0, v[4:5]
	s_mov_b32 s37, 0
	v_mov_b32_e32 v3, v2
	v_mov_b32_e32 v4, v2
	v_mov_b32_e32 v5, v2
	v_mov_b32_e32 v6, v2
	v_mov_b32_e32 v7, v2
	v_mov_b32_e32 v8, v2
	v_mov_b32_e32 v9, v2
	v_mov_b32_e32 v10, v2
	v_mov_b32_e32 v11, v2
	v_mov_b32_e32 v12, v2
	v_mov_b32_e32 v13, v2
	v_mov_b32_e32 v14, v2
	v_mov_b32_e32 v15, v2
	v_mov_b32_e32 v16, v2
	v_mov_b32_e32 v17, v2
	v_mov_b32_e32 v18, v2
	v_mov_b32_e32 v19, v2
	v_mov_b32_e32 v20, v2
	v_mov_b32_e32 v21, v2
	v_mov_b32_e32 v22, v2
	v_mov_b32_e32 v23, v2
	v_mov_b32_e32 v24, v2
	v_mov_b32_e32 v25, v2
	v_mov_b32_e32 v26, v2
	v_mov_b32_e32 v27, v2
	v_mov_b32_e32 v28, v2
	v_mov_b32_e32 v29, v2
	v_mov_b32_e32 v30, v2
	v_mov_b32_e32 v31, v2
	v_mov_b32_e32 v32, v2
	v_mov_b32_e32 v33, v2
	v_mov_b32_e32 v34, v2
	v_mov_b32_e32 v35, v2
	v_mov_b32_e32 v36, v2
	v_mov_b32_e32 v37, v2
	v_mov_b32_e32 v38, v2
	v_mov_b32_e32 v39, v2
	v_mov_b32_e32 v40, v2
	v_mov_b32_e32 v41, v2
	v_mov_b32_e32 v42, v2
	v_mov_b32_e32 v43, v2
	v_mov_b32_e32 v44, v2
	v_mov_b32_e32 v45, v2
	v_mov_b32_e32 v46, v2
	v_mov_b32_e32 v47, v2
	v_mov_b32_e32 v48, v2
	v_mov_b32_e32 v49, v2
	v_mov_b32_e32 v50, v2
	v_mov_b32_e32 v51, v2
	v_mov_b32_e32 v52, v2
	v_mov_b32_e32 v53, v2
	v_mov_b32_e32 v54, v2
	v_mov_b32_e32 v55, v2
	v_mov_b32_e32 v56, v2
	v_mov_b32_e32 v57, v2
	v_mov_b32_e32 v58, v2
	v_mov_b32_e32 v59, v2
	v_mov_b32_e32 v60, v2
	v_mov_b32_e32 v61, v2
	v_mov_b32_e32 v62, v2
	v_mov_b32_e32 v63, v2
	v_mov_b32_e32 v64, v2
	v_mov_b32_e32 v65, v2
	s_waitcnt lgkmcnt(0)
	s_barrier
	ds_read_b128 v[192:195], v161 offset:0
	ds_read_b128 v[196:199], v162 offset:18432
	ds_read_b128 v[200:203], v162 offset:23040
	ds_read_b128 v[204:207], v161 offset:4608
	ds_read_b128 v[208:211], v161 offset:32
	ds_read_b128 v[212:215], v162 offset:18464
	ds_read_b128 v[216:219], v162 offset:23072
	ds_read_b128 v[220:223], v161 offset:4640
	v_subrev_u32_e32 v152, s82, v152
	v_add_u32_e32 v152, v152, v136
	v_subrev_u32_e32 v150, s82, v150
	v_add_u32_e32 v150, v150, v136
	v_subrev_u32_e32 v148, s82, v148
	v_add_u32_e32 v148, v148, v136
	v_subrev_u32_e32 v146, s82, v146
	v_add_u32_e32 v146, v146, v136
	v_subrev_u32_e32 v144, s82, v144
	v_add_u32_e32 v144, v144, v136
	v_subrev_u32_e32 v142, s82, v142
	v_add_u32_e32 v142, v142, v136
	v_subrev_u32_e32 v140, s82, v140
	v_add_u32_e32 v140, v140, v136
	v_subrev_u32_e32 v138, s82, v138
	v_add_u32_e32 v138, v138, v136
	s_add_u32 s84, s82, 0x10740000
	s_addc_u32 s85, s83, 0
	s_add_u32 s86, s82, 0x95d0000
	s_addc_u32 s87, s83, 0
	s_mov_b64 s[88:89], s[4:5]
	s_and_b64 s[88:89], s[88:89], s[6:7]
	s_and_b64 s[88:89], s[88:89], s[8:9]
	s_and_b64 s[88:89], s[88:89], s[10:11]
	s_branch .LBB0_2925

.LBB0_2925:
	s_cmp_gt_u32 s37, 28
	s_waitcnt vmcnt(3)
	ds_write_b128 v154, v[66:69] offset:36864
	ds_write_b128 v154, v[70:73] offset:55296
	s_waitcnt vmcnt(2)
	ds_write_b128 v154, v[78:81] offset:41472
	ds_write_b128 v154, v[74:77] offset:59904
	s_waitcnt vmcnt(1)
	ds_write_b128 v154, v[82:85] offset:46080
	ds_write_b128 v154, v[90:93] offset:64512
	s_waitcnt vmcnt(0)
	ds_write_b128 v154, v[102:105] offset:50688
	ds_write_b128 v156, v[106:109] offset:13824
	s_cbranch_scc1 .LBB0_2935
	s_cmp_eq_u64 s[88:89], exec
	s_cbranch_scc1 .Lgf_11
	global_load_dwordx4 v[66:69], v152, s[84:85] offset:384
	s_and_saveexec_b64 s[20:21], s[4:5]
	s_cbranch_execz .LBB0_2928
	global_load_dwordx4 v[70:73], v150, s[86:87] offset:384

.LBB0_2935:
	s_cmp_gt_u32 s37, 29
	s_cselect_b64 s[20:21], -1, 0
	s_and_b64 vcc, exec, s[20:21]
	s_waitcnt lgkmcnt(4)
	v_mfma_f32_32x32x16_bf16 v[50:65], v[192:195], v[196:199], v[50:65]
	v_mfma_f32_32x32x16_bf16 v[34:49], v[192:195], v[200:203], v[34:49]
	v_mfma_f32_32x32x16_bf16 v[18:33], v[204:207], v[196:199], v[18:33]
	v_mfma_f32_32x32x16_bf16 v[2:17], v[204:207], v[200:203], v[2:17]
	ds_read_b128 v[164:167], v161 offset:64
	ds_read_b128 v[168:171], v162 offset:18496
	ds_read_b128 v[172:175], v162 offset:23104
	ds_read_b128 v[176:179], v161 offset:4672
	s_waitcnt lgkmcnt(4)
	v_mfma_f32_32x32x16_bf16 v[50:65], v[208:211], v[212:215], v[50:65]
	v_mfma_f32_32x32x16_bf16 v[34:49], v[208:211], v[216:219], v[34:49]
	v_mfma_f32_32x32x16_bf16 v[18:33], v[220:223], v[212:215], v[18:33]
	v_mfma_f32_32x32x16_bf16 v[2:17], v[220:223], v[216:219], v[2:17]
	ds_read_b128 v[180:183], v161 offset:96
	ds_read_b128 v[184:187], v162 offset:18528
	ds_read_b128 v[188:191], v162 offset:23136
	ds_read_b128 v[224:227], v161 offset:4704
	s_waitcnt lgkmcnt(4)
	v_mfma_f32_32x32x16_bf16 v[50:65], v[164:167], v[168:171], v[50:65]
	v_mfma_f32_32x32x16_bf16 v[34:49], v[164:167], v[172:175], v[34:49]
	s_waitcnt lgkmcnt(0)
	s_barrier
	ds_read_b128 v[192:195], v161 offset:36864
	ds_read_b128 v[196:199], v162 offset:55296
	ds_read_b128 v[200:203], v162 offset:59904
	ds_read_b128 v[204:207], v161 offset:41472
	ds_read_b128 v[208:211], v161 offset:36896
	ds_read_b128 v[212:215], v162 offset:55328
	ds_read_b128 v[216:219], v162 offset:59936
	ds_read_b128 v[220:223], v161 offset:41504
	v_mfma_f32_32x32x16_bf16 v[18:33], v[176:179], v[168:171], v[18:33]
	v_mfma_f32_32x32x16_bf16 v[2:17], v[176:179], v[172:175], v[2:17]
	v_mfma_f32_32x32x16_bf16 v[50:65], v[180:183], v[184:187], v[50:65]
	v_mfma_f32_32x32x16_bf16 v[34:49], v[180:183], v[188:191], v[34:49]
	v_mfma_f32_32x32x16_bf16 v[18:33], v[224:227], v[184:187], v[18:33]
	v_mfma_f32_32x32x16_bf16 v[2:17], v[224:227], v[188:191], v[2:17]
	s_cbranch_vccnz .LBB0_2924
	s_cmp_gt_u32 s37, 27
	s_waitcnt vmcnt(3)
	ds_write_b128 v154, v[86:89]
	ds_write_b128 v154, v[94:97] offset:18432
	s_waitcnt vmcnt(2)
	ds_write_b128 v154, v[110:113] offset:4608
	ds_write_b128 v154, v[98:101] offset:23040
	s_waitcnt vmcnt(1)
	ds_write_b128 v154, v[114:117] offset:9216
	ds_write_b128 v154, v[118:121] offset:27648
	s_waitcnt vmcnt(0)
	ds_write_b128 v154, v[122:125] offset:13824
	ds_write_b128 v154, v[126:129] offset:32256
	s_cbranch_scc1 .LBB0_2924
	s_cmp_eq_u64 s[88:89], exec
	s_cbranch_scc1 .Lgf_12
	global_load_dwordx4 v[86:89], v152, s[84:85] offset:512
	s_and_saveexec_b64 s[22:23], s[4:5]
	s_cbranch_execz .LBB0_2939
	global_load_dwordx4 v[94:97], v150, s[86:87] offset:512

.LBB0_3121:
	s_or_b64 exec, exec, s[2:3]
	v_add_u32_e32 v2, s33, v194
	v_ashrrev_i32_e32 v3, 31, v2
	v_lshlrev_b64 v[2:3], 11, v[2:3]
	v_lshl_add_u64 v[168:169], s[82:83], 0, v[2:3]
	v_add_u32_e32 v2, s33, v195
	v_ashrrev_i32_e32 v3, 31, v2
	v_lshlrev_b64 v[2:3], 11, v[2:3]
	v_lshl_add_u64 v[172:173], s[82:83], 0, v[2:3]
	v_add_u32_e32 v2, s33, v196
	v_ashrrev_i32_e32 v3, 31, v2
	v_lshlrev_b64 v[2:3], 11, v[2:3]
	v_lshl_add_u64 v[176:177], s[82:83], 0, v[2:3]
	v_add_u32_e32 v2, s33, v1
	v_ashrrev_i32_e32 v3, 31, v2
	v_lshlrev_b64 v[2:3], 11, v[2:3]
	v_lshl_add_u64 v[166:167], s[82:83], 0, v[48:49]
	v_lshl_add_u64 v[170:171], s[82:83], 0, v[42:43]
	v_lshl_add_u64 v[174:175], s[82:83], 0, v[36:37]
	v_lshl_add_u64 v[178:179], s[82:83], 0, v[34:35]
	v_lshl_add_u64 v[180:181], s[82:83], 0, v[2:3]
	s_mov_b32 s35, 0
	v_mov_b32_e32 v51, v50
	v_mov_b32_e32 v52, v50
	v_mov_b32_e32 v53, v50
	v_mov_b32_e32 v54, v50
	v_mov_b32_e32 v55, v50
	v_mov_b32_e32 v56, v50
	v_mov_b32_e32 v57, v50
	v_mov_b32_e32 v58, v50
	v_mov_b32_e32 v59, v50
	v_mov_b32_e32 v60, v50
	v_mov_b32_e32 v61, v50
	v_mov_b32_e32 v62, v50
	v_mov_b32_e32 v63, v50
	v_mov_b32_e32 v64, v50
	v_mov_b32_e32 v65, v50
	v_mov_b32_e32 v34, v50
	v_mov_b32_e32 v35, v50
	v_mov_b32_e32 v36, v50
	v_mov_b32_e32 v37, v50
	v_mov_b32_e32 v38, v50
	v_mov_b32_e32 v39, v50
	v_mov_b32_e32 v40, v50
	v_mov_b32_e32 v41, v50
	v_mov_b32_e32 v42, v50
	v_mov_b32_e32 v43, v50
	v_mov_b32_e32 v44, v50
	v_mov_b32_e32 v45, v50
	v_mov_b32_e32 v46, v50
	v_mov_b32_e32 v47, v50
	v_mov_b32_e32 v48, v50
	v_mov_b32_e32 v49, v50
	v_mov_b32_e32 v18, v50
	v_mov_b32_e32 v19, v50
	v_mov_b32_e32 v20, v50
	v_mov_b32_e32 v21, v50
	v_mov_b32_e32 v22, v50
	v_mov_b32_e32 v23, v50
	v_mov_b32_e32 v24, v50
	v_mov_b32_e32 v25, v50
	v_mov_b32_e32 v26, v50
	v_mov_b32_e32 v27, v50
	v_mov_b32_e32 v28, v50
	v_mov_b32_e32 v29, v50
	v_mov_b32_e32 v30, v50
	v_mov_b32_e32 v31, v50
	v_mov_b32_e32 v32, v50
	v_mov_b32_e32 v33, v50
	v_mov_b32_e32 v2, v50
	v_mov_b32_e32 v3, v50
	v_mov_b32_e32 v4, v50
	v_mov_b32_e32 v5, v50
	v_mov_b32_e32 v6, v50
	v_mov_b32_e32 v7, v50
	v_mov_b32_e32 v8, v50
	v_mov_b32_e32 v9, v50
	v_mov_b32_e32 v10, v50
	v_mov_b32_e32 v11, v50
	v_mov_b32_e32 v12, v50
	v_mov_b32_e32 v13, v50
	v_mov_b32_e32 v14, v50
	v_mov_b32_e32 v15, v50
	v_mov_b32_e32 v16, v50
	v_mov_b32_e32 v17, v50
	s_waitcnt lgkmcnt(0)
	s_barrier
	ds_read_b128 v[206:209], v203 offset:0
	ds_read_b128 v[210:213], v204 offset:18432
	ds_read_b128 v[214:217], v204 offset:23040
	ds_read_b128 v[218:221], v203 offset:4608
	ds_read_b128 v[222:225], v203 offset:32
	ds_read_b128 v[226:229], v204 offset:18464
	ds_read_b128 v[230:233], v204 offset:23072
	ds_read_b128 v[234:237], v203 offset:4640
	v_subrev_u32_e32 v180, s82, v180
	v_add_u32_e32 v180, v180, v138
	v_subrev_u32_e32 v178, s82, v178
	v_add_u32_e32 v178, v178, v138
	v_subrev_u32_e32 v176, s82, v176
	v_add_u32_e32 v176, v176, v138
	v_subrev_u32_e32 v174, s82, v174
	v_add_u32_e32 v174, v174, v138
	v_subrev_u32_e32 v172, s82, v172
	v_add_u32_e32 v172, v172, v138
	v_subrev_u32_e32 v170, s82, v170
	v_add_u32_e32 v170, v170, v138
	v_subrev_u32_e32 v168, s82, v168
	v_add_u32_e32 v168, v168, v138
	v_subrev_u32_e32 v166, s82, v166
	v_add_u32_e32 v166, v166, v138
	s_add_u32 s84, s82, 0x149c0000
	s_addc_u32 s85, s83, 0
	s_add_u32 s86, s82, 0x9dd0000
	s_addc_u32 s87, s83, 0
	s_mov_b64 s[88:89], s[12:13]
	s_and_b64 s[88:89], s[88:89], s[14:15]
	s_and_b64 s[88:89], s[88:89], s[16:17]
	s_and_b64 s[88:89], s[88:89], s[18:19]
	s_branch .LBB0_3124
